# GEMM loops: first trip peeled with SrcC=0 on the first MFMA of each accumulator; accumulator zero-init and zero-fragment MFMAs removed
# speedup vs baseline: 1.0427x; 1.0009x over previous
.LBB0_121:
	s_abs_i32 s4, s0
	v_readlane_b32 s5, v254, 29
	s_mul_hi_u32 s5, s4, s5
	s_mul_i32 s6, s5, s8
	s_sub_i32 s4, s4, s6
	s_ashr_i32 s1, s0, 31
	s_add_i32 s6, s5, 1
	s_sub_i32 s7, s4, s8
	s_cmp_ge_u32 s4, s8
	s_cselect_b32 s5, s6, s5
	s_cselect_b32 s4, s7, s4
	s_add_i32 s6, s5, 1
	s_cmp_ge_u32 s4, s8
	s_cselect_b32 s4, s6, s5
	s_xor_b32 s4, s4, s1
	s_sub_i32 s4, s4, s1
	s_lshr_b32 s1, s1, 30
	s_add_i32 s1, s0, s1
	s_ashr_i32 s5, s1, 2
	s_abs_i32 s5, s5
	v_readlane_b32 s7, v254, 31
	s_mul_hi_u32 s7, s5, s7
	v_readlane_b32 s8, v254, 30
	s_mul_i32 s7, s7, s8
	s_and_b32 s6, s1, 0xfffffc
	s_sub_i32 s5, s5, s7
	s_sub_i32 s6, s0, s6
	s_ashr_i32 s1, s1, 31
	s_sub_i32 s7, s5, s8
	s_cmp_ge_u32 s5, s8
	s_cselect_b32 s5, s7, s5
	s_sub_i32 s7, s5, s8
	s_cmp_ge_u32 s5, s8
	s_cselect_b32 s5, s7, s5
	s_xor_b32 s5, s5, s1
	s_sub_i32 s1, s5, s1
	v_readlane_b32 s5, v254, 25
	s_add_i32 s5, s5, s1
	s_lshl_b32 s1, s4, 10
	s_lshl_b32 s4, s6, 8
	v_mov_b32_e32 v203, v208
	v_readlane_b32 s6, v253, 28
	s_add_i32 s1, s1, s4
	v_readlane_b32 s7, v253, 29
	v_ashrrev_i32_e32 v4, 2, v203
	s_mul_i32 s4, s5, 0xc0
	v_add_u32_e32 v2, s1, v4
	v_mov_b64_e32 v[0:1], s[6:7]
	s_movk_i32 s5, 0x1600
	v_mad_i64_i32 v[0:1], s[6:7], v2, s5, v[0:1]
	v_lshlrev_b32_e32 v5, 4, v203
	v_readlane_b32 s6, v253, 61
	v_and_b32_e32 v192, 48, v5
	v_readlane_b32 s7, v253, 62
	v_lshl_add_u64 v[100:101], v[0:1], 0, v[192:193]
	v_add_u32_e32 v2, s4, v4
	v_mov_b64_e32 v[0:1], s[6:7]
	v_mad_i64_i32 v[0:1], s[6:7], v2, s5, v[0:1]
	s_mov_b32 s5, 0x58000
	v_add_co_u32_e32 v8, vcc, s5, v100
	s_mov_b32 s6, 0xb0000
	s_nop 0
	v_addc_co_u32_e32 v9, vcc, 0, v101, vcc
	v_add_co_u32_e32 v12, vcc, s6, v100
	s_mov_b32 s7, 0x108000
	s_nop 0
	v_addc_co_u32_e32 v13, vcc, 0, v101, vcc
	v_add_co_u32_e32 v16, vcc, s7, v100
	v_lshl_add_u64 v[102:103], v[0:1], 0, v[192:193]
	s_nop 0
	v_addc_co_u32_e32 v17, vcc, 0, v101, vcc
	v_bfe_u32 v6, v203, 5, 1
	v_lshrrev_b32_e32 v7, 2, v203
	v_bfe_u32 v10, v203, 2, 2
	v_add_co_u32_e32 v24, vcc, s5, v102
	v_lshlrev_b32_e32 v11, 1, v203
	v_bitop3_b32 v7, v6, v7, 3 bitop3:0x78
	v_bitop3_b32 v6, v6, v10, 2 bitop3:0x36
	v_and_b32_e32 v10, 0xffffffe0, v4
	v_addc_co_u32_e32 v25, vcc, 0, v103, vcc
	v_and_b32_e32 v192, 31, v203
	v_and_b32_e32 v204, 0x80, v11
	v_lshl_add_u32 v205, v10, 1, v10
	v_add_co_u32_e32 v28, vcc, s6, v102
	v_or_b32_e32 v11, v204, v192
	v_or_b32_e32 v10, v205, v192
	global_load_dwordx4 v[0:3], v[100:101], off
	global_load_dwordx4 v[32:35], v[8:9], off
	global_load_dwordx4 v[36:39], v[12:13], off
	global_load_dwordx4 v[40:43], v[16:17], off
	global_load_dwordx4 v[44:47], v[102:103], off
	v_addc_co_u32_e32 v29, vcc, 0, v103, vcc
	v_bitop3_b32 v5, v5, 48, v203 bitop3:0x48
	v_lshlrev_b32_e32 v11, 6, v11
	v_lshlrev_b32_e32 v7, 4, v7
	v_lshlrev_b32_e32 v6, 4, v6
	v_lshl_add_u32 v10, v10, 6, v214
	global_load_dwordx4 v[48:51], v[24:25], off
	global_load_dwordx4 v[52:55], v[28:29], off
	v_or_b32_e32 v114, v11, v7
	v_or_b32_e32 v115, v11, v6
	v_or_b32_e32 v116, v10, v7
	v_or_b32_e32 v117, v10, v6
	v_lshl_or_b32 v118, v4, 6, v5
	global_load_dwordx4 v[4:7], v[100:101], off offset:64
	s_nop 0
	global_load_dwordx4 v[8:11], v[8:9], off offset:64
	s_nop 0
	global_load_dwordx4 v[12:15], v[12:13], off offset:64
	s_nop 0
	global_load_dwordx4 v[16:19], v[16:17], off offset:64
	s_nop 0
	global_load_dwordx4 v[20:23], v[102:103], off offset:64
	s_nop 0
	global_load_dwordx4 v[24:27], v[24:25], off offset:64
	s_nop 0
	global_load_dwordx4 v[28:31], v[28:29], off offset:64
	v_accvgpr_mov_b32 a193, a192
	v_accvgpr_mov_b32 a194, a192
	v_accvgpr_mov_b32 a195, a192
	v_accvgpr_mov_b32 a196, a192
	v_accvgpr_mov_b32 a197, a192
	v_accvgpr_mov_b32 a198, a192
	v_accvgpr_mov_b32 a199, a192
	v_accvgpr_mov_b32 a200, a192
	v_accvgpr_mov_b32 a201, a192
	v_accvgpr_mov_b32 a202, a192
	v_accvgpr_mov_b32 a203, a192
	v_accvgpr_mov_b32 a204, a192
	v_accvgpr_mov_b32 a205, a192
	v_accvgpr_mov_b32 a206, a192
	v_accvgpr_mov_b32 a207, a192


	s_waitcnt vmcnt(13)
	ds_write_b128 v118, v[0:3] offset:0
	s_waitcnt vmcnt(12)
	ds_write_b128 v118, v[32:35] offset:0x1000
	s_waitcnt vmcnt(11)
	ds_write_b128 v118, v[36:39] offset:0x2000
	s_mov_b64 s[8:9], 0x58000
	s_mov_b64 s[10:11], 0xb0000
	s_waitcnt vmcnt(10)
	ds_write_b128 v118, v[40:43] offset:0x3000
	s_waitcnt vmcnt(9)
	ds_write_b128 v118, v[44:47] offset:0x4000
	s_waitcnt vmcnt(8)
	ds_write_b128 v118, v[48:51] offset:0x5000
	s_waitcnt vmcnt(7)
	ds_write_b128 v118, v[52:55] offset:0x6000
	s_waitcnt lgkmcnt(0)
	s_mov_b64 s[12:13], 0x108000
	v_mov_b32_e32 v0, 0
	v_lshl_add_u64 v[104:105], v[100:101], 0, s[8:9]
	s_mov_b32 s6, 0
	v_lshl_add_u64 v[106:107], v[100:101], 0, s[10:11]
	v_lshl_add_u64 v[108:109], v[100:101], 0, s[12:13]
	v_lshl_add_u64 v[110:111], v[102:103], 0, s[8:9]
	v_lshl_add_u64 v[112:113], v[102:103], 0, s[10:11]
	s_mov_b32 s5, -2
	v_mov_b32_e32 v1, v0
	v_mov_b32_e32 v2, v0
	v_mov_b32_e32 v3, v0
	v_mov_b32_e32 v194, v0
	v_mov_b32_e32 v195, v0
	v_mov_b32_e32 v196, v0
	v_mov_b32_e32 v197, v0
	v_mov_b32_e32 v32, v0
	v_mov_b32_e32 v33, v0
	v_mov_b32_e32 v34, v0
	v_mov_b32_e32 v35, v0
	s_barrier
.LBB0_122:
	v_readfirstlane_b32 s10, v100
	v_readfirstlane_b32 s11, v101
	v_readfirstlane_b32 s12, v104
	v_readfirstlane_b32 s13, v105
	v_readfirstlane_b32 s14, v106
	v_readfirstlane_b32 s15, v107
	v_readfirstlane_b32 s16, v108
	v_readfirstlane_b32 s17, v109
	v_readfirstlane_b32 s18, v102
	v_readfirstlane_b32 s19, v103
	v_readfirstlane_b32 s20, v110
	v_readfirstlane_b32 s21, v111
	v_readfirstlane_b32 s22, v112
	v_readfirstlane_b32 s23, v113
	v_subrev_u32_e32 v140, s10, v100
	v_subrev_u32_e32 v141, s18, v102
	s_nop 4
	s_add_i32 s7, s6, 64
	s_min_u32 s8, s7, 0xae0
	s_lshl_b32 s78, s8, 1
	ds_read_b128 v[52:55], v116 offset:0
	ds_read_b128 v[48:51], v116 offset:0x800
	ds_read_b128 v[44:47], v116 offset:0x1000
	ds_read_b128 v[96:99], v114 offset:0
	ds_read_b128 v[92:95], v114 offset:0x800
	ds_read_b128 v[88:91], v114 offset:0x1000
	v_add_u32_e32 v142, s78, v140
	v_add_u32_e32 v143, s78, v141
	global_load_dwordx4 v[64:67], v142, s[10:11]
	ds_read_b128 v[56:59], v114 offset:0x1800
	global_load_dwordx4 v[60:63], v142, s[12:13]
	global_load_dwordx4 v[72:75], v142, s[14:15]
	global_load_dwordx4 v[68:71], v142, s[16:17]
	global_load_dwordx4 v[84:87], v143, s[18:19]
	s_waitcnt lgkmcnt(3)
	v_mfma_f32_32x32x16_bf16 a[48:63], v[96:99], v[52:55], 0
	ds_read_b128 v[36:39], v117 offset:0
	v_mfma_f32_32x32x16_bf16 a[64:79], v[96:99], v[48:51], 0
	global_load_dwordx4 v[76:79], v143, s[20:21]
	v_mfma_f32_32x32x16_bf16 a[80:95], v[96:99], v[44:47], 0
	ds_read_b128 v[40:43], v117 offset:0x800
	s_waitcnt lgkmcnt(4)
	v_mfma_f32_32x32x16_bf16 a[96:111], v[92:95], v[52:55], 0
	global_load_dwordx4 v[80:83], v143, s[22:23]
	v_mfma_f32_32x32x16_bf16 a[112:127], v[92:95], v[48:51], 0
	ds_read_b128 v[120:123], v117 offset:0x1000
	v_mfma_f32_32x32x16_bf16 a[128:143], v[92:95], v[44:47], 0
	ds_read_b128 v[124:127], v115 offset:0
	s_waitcnt lgkmcnt(5)
	v_mfma_f32_32x32x16_bf16 a[144:159], v[88:91], v[52:55], 0
	ds_read_b128 v[128:131], v115 offset:0x800
	s_min_u32 s6, s6, 0xa80
	s_lshl_b32 s78, s6, 1
	v_mfma_f32_32x32x16_bf16 a[160:175], v[88:91], v[48:51], 0
	ds_read_b128 v[132:135], v115 offset:0x1000
	s_add_i32 s8, s78, 0xc0
	s_mov_b32 s9, s79
	v_mfma_f32_32x32x16_bf16 a[176:191], v[88:91], v[44:47], 0
	ds_read_b128 v[136:139], v115 offset:0x1800
	s_add_i32 s5, s5, 2
	s_cmpk_lt_u32 s5, 0x56
	s_waitcnt lgkmcnt(7)
	v_mfma_f32_32x32x16_bf16 a[32:47], v[56:59], v[52:55], 0
	s_waitcnt vmcnt(13)
	ds_write_b128 v118, v[4:7] offset:0x8000
	v_mfma_f32_32x32x16_bf16 a[16:31], v[56:59], v[48:51], 0
	s_waitcnt vmcnt(12)
	ds_write_b128 v118, v[8:11] offset:0x9000
	v_mfma_f32_32x32x16_bf16 a[0:15], v[56:59], v[44:47], 0
	s_waitcnt vmcnt(11)
	ds_write_b128 v118, v[12:15] offset:0xa000
	s_waitcnt lgkmcnt(6)
	v_mfma_f32_32x32x16_bf16 a[48:63], v[124:127], v[36:39], a[48:63]
	s_waitcnt vmcnt(10)
	ds_write_b128 v118, v[16:19] offset:0xb000
	v_mfma_f32_32x32x16_bf16 a[64:79], v[124:127], v[40:43], a[64:79]
	s_waitcnt vmcnt(9)
	ds_write_b128 v118, v[20:23] offset:0xc000
	v_mfma_f32_32x32x16_bf16 a[80:95], v[124:127], v[120:123], a[80:95]
	s_waitcnt vmcnt(8)
	ds_write_b128 v118, v[24:27] offset:0xd000
	s_waitcnt lgkmcnt(8)
	v_mfma_f32_32x32x16_bf16 a[96:111], v[128:131], v[36:39], a[96:111]
	s_waitcnt vmcnt(7)
	ds_write_b128 v118, v[28:31] offset:0xe000
	v_mfma_f32_32x32x16_bf16 a[112:127], v[128:131], v[40:43], a[112:127]
	v_mfma_f32_32x32x16_bf16 a[128:143], v[128:131], v[120:123], a[128:143]
	s_waitcnt lgkmcnt(0)
	s_barrier
	ds_read_b128 v[44:47], v116 offset:0x8000
	ds_read_b128 v[48:51], v116 offset:0x8800
	ds_read_b128 v[52:55], v116 offset:0x9000
	ds_read_b128 v[56:59], v114 offset:0x8000
	v_mfma_f32_32x32x16_bf16 a[144:159], v[132:135], v[36:39], a[144:159]
	ds_read_b128 v[88:91], v114 offset:0x8800
	v_mfma_f32_32x32x16_bf16 a[160:175], v[132:135], v[40:43], a[160:175]
	ds_read_b128 v[92:95], v114 offset:0x9000
	v_add_u32_e32 v142, s8, v140
	v_add_u32_e32 v143, s8, v141
	global_load_dwordx4 v[4:7], v142, s[10:11]
	v_mfma_f32_32x32x16_bf16 a[176:191], v[132:135], v[120:123], a[176:191]
	ds_read_b128 v[96:99], v114 offset:0x9800
	global_load_dwordx4 v[8:11], v142, s[12:13]
	v_mfma_f32_32x32x16_bf16 a[32:47], v[136:139], v[36:39], a[32:47]
	global_load_dwordx4 v[12:15], v142, s[14:15]
	v_mfma_f32_32x32x16_bf16 a[16:31], v[136:139], v[40:43], a[16:31]
	global_load_dwordx4 v[16:19], v142, s[16:17]
	v_mfma_f32_32x32x16_bf16 a[0:15], v[136:139], v[120:123], a[0:15]
	global_load_dwordx4 v[20:23], v143, s[18:19]
	s_waitcnt lgkmcnt(3)
	v_mfma_f32_32x32x16_bf16 a[48:63], v[56:59], v[44:47], a[48:63]
	ds_read_b128 v[40:43], v117 offset:0x8000
	v_mfma_f32_32x32x16_bf16 a[64:79], v[56:59], v[48:51], a[64:79]
	global_load_dwordx4 v[24:27], v143, s[20:21]
	v_mfma_f32_32x32x16_bf16 a[80:95], v[56:59], v[52:55], a[80:95]
	ds_read_b128 v[36:39], v117 offset:0x8800
	s_waitcnt lgkmcnt(4)
	v_mfma_f32_32x32x16_bf16 a[96:111], v[88:91], v[44:47], a[96:111]
	global_load_dwordx4 v[28:31], v143, s[22:23]
	v_mfma_f32_32x32x16_bf16 a[112:127], v[88:91], v[48:51], a[112:127]
	ds_read_b128 v[194:197], v117 offset:0x9000
	v_mfma_f32_32x32x16_bf16 a[128:143], v[88:91], v[52:55], a[128:143]
	ds_read_b128 v[120:123], v115 offset:0x8000
	s_waitcnt lgkmcnt(5)
	v_mfma_f32_32x32x16_bf16 a[144:159], v[92:95], v[44:47], a[144:159]
	ds_read_b128 v[124:127], v115 offset:0x8800
	v_mfma_f32_32x32x16_bf16 a[160:175], v[92:95], v[48:51], a[160:175]
	ds_read_b128 v[128:131], v115 offset:0x9000
	v_mfma_f32_32x32x16_bf16 a[176:191], v[92:95], v[52:55], a[176:191]
	ds_read_b128 v[198:201], v115 offset:0x9800
	s_waitcnt lgkmcnt(7)
	v_mfma_f32_32x32x16_bf16 a[32:47], v[96:99], v[44:47], a[32:47]
	s_waitcnt vmcnt(13)
	ds_write_b128 v118, v[64:67] offset:0
	v_mfma_f32_32x32x16_bf16 a[16:31], v[96:99], v[48:51], a[16:31]
	s_waitcnt vmcnt(12)
	ds_write_b128 v118, v[60:63] offset:0x1000
	v_mfma_f32_32x32x16_bf16 a[0:15], v[96:99], v[52:55], a[0:15]
	s_waitcnt vmcnt(11)
	ds_write_b128 v118, v[72:75] offset:0x2000
	s_waitcnt lgkmcnt(6)
	v_mfma_f32_32x32x16_bf16 a[48:63], v[120:123], v[40:43], a[48:63]
	s_waitcnt vmcnt(10)
	ds_write_b128 v118, v[68:71] offset:0x3000
	v_mfma_f32_32x32x16_bf16 a[64:79], v[120:123], v[36:39], a[64:79]
	s_waitcnt vmcnt(9)
	ds_write_b128 v118, v[84:87] offset:0x4000
	v_mfma_f32_32x32x16_bf16 a[80:95], v[120:123], v[194:197], a[80:95]
	s_waitcnt vmcnt(8)
	ds_write_b128 v118, v[76:79] offset:0x5000
	s_waitcnt lgkmcnt(8)
	v_mfma_f32_32x32x16_bf16 a[96:111], v[124:127], v[40:43], a[96:111]
	s_waitcnt vmcnt(7)
	ds_write_b128 v118, v[80:83] offset:0x6000
	v_mfma_f32_32x32x16_bf16 a[112:127], v[124:127], v[36:39], a[112:127]
	v_mfma_f32_32x32x16_bf16 a[128:143], v[124:127], v[194:197], a[128:143]
	s_waitcnt lgkmcnt(0)
	s_barrier
	s_mov_b32 s6, s7

.LBB0_140:
	s_abs_i32 s2, s0
	v_readlane_b32 s3, v254, 36
	s_mul_hi_u32 s3, s2, s3
	s_mul_i32 s4, s3, s6
	s_sub_i32 s2, s2, s4
	s_ashr_i32 s1, s0, 31
	s_add_i32 s4, s3, 1
	s_sub_i32 s5, s2, s6
	s_cmp_ge_u32 s2, s6
	s_cselect_b32 s3, s4, s3
	s_cselect_b32 s2, s5, s2
	s_add_i32 s4, s3, 1
	s_cmp_ge_u32 s2, s6
	s_cselect_b32 s2, s4, s3
	s_xor_b32 s2, s2, s1
	s_sub_i32 s2, s2, s1
	s_lshr_b32 s1, s1, 30
	s_add_i32 s1, s0, s1
	s_ashr_i32 s3, s1, 2
	s_abs_i32 s3, s3
	v_readlane_b32 s5, v254, 38
	s_mul_hi_u32 s5, s3, s5
	v_readlane_b32 s6, v254, 37
	s_mul_i32 s5, s5, s6
	s_and_b32 s4, s1, 0xfffffc
	s_sub_i32 s3, s3, s5
	s_sub_i32 s4, s0, s4
	s_ashr_i32 s1, s1, 31
	s_sub_i32 s5, s3, s6
	s_cmp_ge_u32 s3, s6
	s_cselect_b32 s3, s5, s3
	s_sub_i32 s5, s3, s6
	s_cmp_ge_u32 s3, s6
	s_cselect_b32 s3, s5, s3
	s_xor_b32 s3, s3, s1
	s_sub_i32 s1, s3, s1
	v_readlane_b32 s3, v254, 32
	s_add_i32 s3, s3, s1
	s_lshl_b32 s1, s2, 10
	s_lshl_b32 s2, s4, 8
	v_mov_b32_e32 v136, v208
	v_readlane_b32 s4, v253, 28
	s_add_i32 s1, s1, s2
	v_readlane_b32 s5, v253, 29
	v_ashrrev_i32_e32 v4, 2, v136
	s_lshl_b32 s2, s3, 7
	v_add_u32_e32 v2, s1, v4
	v_mov_b64_e32 v[0:1], s[4:5]
	s_movk_i32 s3, 0x1600
	v_mad_i64_i32 v[0:1], s[4:5], v2, s3, v[0:1]
	v_lshlrev_b32_e32 v5, 4, v136
	v_readlane_b32 s4, v253, 61
	s_addk_i32 s2, 0x3000
	v_and_b32_e32 v192, 48, v5
	v_readlane_b32 s5, v253, 62
	v_lshl_add_u64 v[68:69], v[0:1], 0, v[192:193]
	v_add_u32_e32 v2, s2, v4
	v_mov_b64_e32 v[0:1], s[4:5]
	v_mad_i64_i32 v[0:1], s[4:5], v2, s3, v[0:1]
	s_mov_b32 s3, 0x58000
	v_add_co_u32_e32 v8, vcc, s3, v68
	s_mov_b32 s4, 0xb0000
	s_nop 0
	v_addc_co_u32_e32 v9, vcc, 0, v69, vcc
	v_add_co_u32_e32 v12, vcc, s4, v68
	s_mov_b32 s4, 0x108000
	s_nop 0
	v_addc_co_u32_e32 v13, vcc, 0, v69, vcc
	v_bfe_u32 v6, v136, 5, 1
	v_lshrrev_b32_e32 v7, 2, v136
	v_bfe_u32 v10, v136, 2, 2
	v_add_co_u32_e32 v16, vcc, s4, v68
	v_lshlrev_b32_e32 v11, 1, v136
	v_bitop3_b32 v7, v6, v7, 3 bitop3:0x78
	v_bitop3_b32 v6, v6, v10, 2 bitop3:0x36
	v_ashrrev_i32_e32 v10, 1, v136
	v_lshl_add_u64 v[70:71], v[0:1], 0, v[192:193]
	v_addc_co_u32_e32 v17, vcc, 0, v69, vcc
	v_and_b32_e32 v137, 31, v136
	s_waitcnt vmcnt(7)
	v_and_b32_e32 v138, 0x80, v11
	v_and_b32_e32 v139, 0xffffffc0, v10
	v_add_co_u32_e32 v24, vcc, s3, v70
	v_or_b32_e32 v11, v138, v137
	v_or_b32_e32 v10, v139, v137
	global_load_dwordx4 v[0:3], v[68:69], off
	global_load_dwordx4 v[28:31], v[8:9], off
	global_load_dwordx4 v[32:35], v[12:13], off
	global_load_dwordx4 v[36:39], v[16:17], off
	global_load_dwordx4 v[40:43], v[70:71], off
	v_addc_co_u32_e32 v25, vcc, 0, v71, vcc
	v_bitop3_b32 v5, v5, 48, v136 bitop3:0x48
	v_lshlrev_b32_e32 v11, 6, v11
	v_lshlrev_b32_e32 v7, 4, v7
	v_lshlrev_b32_e32 v6, 4, v6
	v_lshl_add_u32 v10, v10, 6, v214
	global_load_dwordx4 v[44:47], v[24:25], off
	v_or_b32_e32 v80, v11, v7
	v_or_b32_e32 v81, v11, v6
	v_or_b32_e32 v82, v10, v7
	v_or_b32_e32 v83, v10, v6
	v_lshl_or_b32 v84, v4, 6, v5
	global_load_dwordx4 v[4:7], v[68:69], off offset:64
	s_nop 0
	global_load_dwordx4 v[8:11], v[8:9], off offset:64
	s_nop 0
	global_load_dwordx4 v[12:15], v[12:13], off offset:64
	s_nop 0
	global_load_dwordx4 v[16:19], v[16:17], off offset:64
	s_nop 0
	global_load_dwordx4 v[20:23], v[70:71], off offset:64
	s_nop 0
	global_load_dwordx4 v[24:27], v[24:25], off offset:64
	v_accvgpr_mov_b32 a193, a192
	v_accvgpr_mov_b32 a194, a192
	v_accvgpr_mov_b32 a195, a192
	v_accvgpr_mov_b32 a196, a192
	v_accvgpr_mov_b32 a197, a192
	v_accvgpr_mov_b32 a198, a192
	v_accvgpr_mov_b32 a199, a192
	v_accvgpr_mov_b32 a200, a192
	v_accvgpr_mov_b32 a201, a192
	v_accvgpr_mov_b32 a202, a192
	v_accvgpr_mov_b32 a203, a192
	v_accvgpr_mov_b32 a204, a192
	v_accvgpr_mov_b32 a205, a192
	v_accvgpr_mov_b32 a206, a192
	v_accvgpr_mov_b32 a207, a192


	s_waitcnt vmcnt(11)
	ds_write_b128 v84, v[0:3] offset:0
	s_waitcnt vmcnt(10)
	ds_write_b128 v84, v[28:31] offset:0x1000
	s_waitcnt vmcnt(9)
	ds_write_b128 v84, v[32:35] offset:0x2000
	s_mov_b64 s[8:9], 0xb0000
	s_mov_b64 s[6:7], 0x58000
	v_lshl_add_u64 v[74:75], v[68:69], 0, s[8:9]
	s_mov_b64 s[8:9], 0x108000
	v_mov_b32_e32 v0, 0
	s_waitcnt vmcnt(8)
	ds_write_b128 v84, v[36:39] offset:0x3000
	s_waitcnt vmcnt(7)
	ds_write_b128 v84, v[40:43] offset:0x4000
	s_waitcnt vmcnt(6)
	ds_write_b128 v84, v[44:47] offset:0x5000
	s_waitcnt lgkmcnt(0)
	v_lshl_add_u64 v[72:73], v[68:69], 0, s[6:7]
	s_mov_b32 s4, 0
	v_lshl_add_u64 v[76:77], v[68:69], 0, s[8:9]
	v_lshl_add_u64 v[78:79], v[70:71], 0, s[6:7]
	s_mov_b32 s3, -2
	v_mov_b32_e32 v1, v0
	v_mov_b32_e32 v2, v0
	v_mov_b32_e32 v3, v0
	v_mov_b32_e32 v28, v0
	v_mov_b32_e32 v29, v0
	v_mov_b32_e32 v30, v0
	v_mov_b32_e32 v31, v0
	v_mov_b32_e32 v32, v0
	v_mov_b32_e32 v33, v0
	v_mov_b32_e32 v34, v0
	v_mov_b32_e32 v35, v0
	v_mov_b32_e32 v36, v0
	v_mov_b32_e32 v37, v0
	v_mov_b32_e32 v38, v0
	v_mov_b32_e32 v39, v0
	s_barrier
.LBB0_141:
	v_readfirstlane_b32 s8, v68
	v_readfirstlane_b32 s9, v69
	v_readfirstlane_b32 s10, v72
	v_readfirstlane_b32 s11, v73
	v_readfirstlane_b32 s12, v74
	v_readfirstlane_b32 s13, v75
	v_readfirstlane_b32 s14, v76
	v_readfirstlane_b32 s15, v77
	v_readfirstlane_b32 s16, v70
	v_readfirstlane_b32 s17, v71
	v_readfirstlane_b32 s18, v78
	v_readfirstlane_b32 s19, v79
	v_subrev_u32_e32 v144, s8, v68
	v_subrev_u32_e32 v145, s16, v70
	s_nop 4
	s_add_i32 s5, s4, 64
	s_min_u32 s6, s5, 0xae0
	s_lshl_b32 s78, s6, 1
	ds_read_b128 v[48:51], v82 offset:0
	ds_read_b128 v[44:47], v82 offset:0x800
	ds_read_b128 v[64:67], v80 offset:0
	ds_read_b128 v[60:63], v80 offset:0x800
	ds_read_b128 v[56:59], v80 offset:0x1000
	v_add_u32_e32 v146, s78, v144
	v_add_u32_e32 v147, s78, v145
	global_load_dwordx4 v[106:109], v146, s[8:9]
	ds_read_b128 v[52:55], v80 offset:0x1800
	global_load_dwordx4 v[110:113], v146, s[10:11]
	global_load_dwordx4 v[114:117], v146, s[12:13]
	s_waitcnt lgkmcnt(3)
	v_mfma_f32_32x32x16_bf16 a[32:47], v[64:67], v[48:51], 0
	ds_read_b128 v[40:43], v83 offset:0
	v_mfma_f32_32x32x16_bf16 a[48:63], v[64:67], v[44:47], 0
	global_load_dwordx4 v[118:121], v146, s[14:15]
	s_waitcnt lgkmcnt(3)
	v_mfma_f32_32x32x16_bf16 a[64:79], v[60:63], v[48:51], 0
	ds_read_b128 v[86:89], v83 offset:0x800
	v_mfma_f32_32x32x16_bf16 a[80:95], v[60:63], v[44:47], 0
	global_load_dwordx4 v[122:125], v147, s[16:17]
	s_waitcnt lgkmcnt(3)
	v_mfma_f32_32x32x16_bf16 a[96:111], v[56:59], v[48:51], 0
	ds_read_b128 v[90:93], v81 offset:0
	v_mfma_f32_32x32x16_bf16 a[112:127], v[56:59], v[44:47], 0
	global_load_dwordx4 v[140:143], v147, s[18:19]
	s_waitcnt vmcnt(11)
	ds_write_b128 v84, v[4:7] offset:0x8000
	s_waitcnt lgkmcnt(4)
	v_mfma_f32_32x32x16_bf16 a[16:31], v[52:55], v[48:51], 0
	ds_read_b128 v[94:97], v81 offset:0x800
	s_min_u32 s4, s4, 0xa80
	s_lshl_b32 s78, s4, 1
	s_waitcnt vmcnt(10)
	ds_write_b128 v84, v[8:11] offset:0x9000
	v_mfma_f32_32x32x16_bf16 a[0:15], v[52:55], v[44:47], 0
	ds_read_b128 v[98:101], v81 offset:0x1000
	s_add_i32 s6, s78, 0xc0
	s_mov_b32 s7, s79
	s_waitcnt vmcnt(9)
	ds_write_b128 v84, v[12:15] offset:0xa000
	s_waitcnt lgkmcnt(5)
	v_mfma_f32_32x32x16_bf16 a[32:47], v[90:93], v[40:43], a[32:47]
	ds_read_b128 v[102:105], v81 offset:0x1800
	s_add_i32 s3, s3, 2
	s_cmpk_lt_u32 s3, 0x56
	s_waitcnt vmcnt(8)
	ds_write_b128 v84, v[16:19] offset:0xb000
	v_mfma_f32_32x32x16_bf16 a[48:63], v[90:93], v[86:89], a[48:63]
	s_waitcnt vmcnt(7)
	ds_write_b128 v84, v[20:23] offset:0xc000
	s_waitcnt lgkmcnt(6)
	v_mfma_f32_32x32x16_bf16 a[64:79], v[94:97], v[40:43], a[64:79]
	s_waitcnt vmcnt(6)
	ds_write_b128 v84, v[24:27] offset:0xd000
	v_mfma_f32_32x32x16_bf16 a[80:95], v[94:97], v[86:89], a[80:95]
	s_waitcnt lgkmcnt(0)
	s_barrier
	ds_read_b128 v[44:47], v82 offset:0x8000
	ds_read_b128 v[48:51], v82 offset:0x8800
	ds_read_b128 v[52:55], v80 offset:0x8000
	v_mfma_f32_32x32x16_bf16 a[96:111], v[98:101], v[40:43], a[96:111]
	ds_read_b128 v[56:59], v80 offset:0x8800
	v_mfma_f32_32x32x16_bf16 a[112:127], v[98:101], v[86:89], a[112:127]
	ds_read_b128 v[60:63], v80 offset:0x9000
	v_add_u32_e32 v146, s6, v144
	v_add_u32_e32 v147, s6, v145
	global_load_dwordx4 v[4:7], v146, s[8:9]
	v_mfma_f32_32x32x16_bf16 a[16:31], v[102:105], v[40:43], a[16:31]
	ds_read_b128 v[64:67], v80 offset:0x9800
	global_load_dwordx4 v[8:11], v146, s[10:11]
	v_mfma_f32_32x32x16_bf16 a[0:15], v[102:105], v[86:89], a[0:15]
	global_load_dwordx4 v[12:15], v146, s[12:13]
	s_waitcnt lgkmcnt(3)
	v_mfma_f32_32x32x16_bf16 a[32:47], v[52:55], v[44:47], a[32:47]
	ds_read_b128 v[40:43], v83 offset:0x8000
	v_mfma_f32_32x32x16_bf16 a[48:63], v[52:55], v[48:51], a[48:63]
	global_load_dwordx4 v[16:19], v146, s[14:15]
	s_waitcnt lgkmcnt(3)
	v_mfma_f32_32x32x16_bf16 a[64:79], v[56:59], v[44:47], a[64:79]
	ds_read_b128 v[128:131], v83 offset:0x8800
	v_mfma_f32_32x32x16_bf16 a[80:95], v[56:59], v[48:51], a[80:95]
	global_load_dwordx4 v[20:23], v147, s[16:17]
	s_waitcnt lgkmcnt(3)
	v_mfma_f32_32x32x16_bf16 a[96:111], v[60:63], v[44:47], a[96:111]
	ds_read_b128 v[86:89], v81 offset:0x8000
	v_mfma_f32_32x32x16_bf16 a[112:127], v[60:63], v[48:51], a[112:127]
	global_load_dwordx4 v[24:27], v147, s[18:19]
	s_waitcnt vmcnt(11)
	ds_write_b128 v84, v[106:109] offset:0
	s_waitcnt lgkmcnt(4)
	v_mfma_f32_32x32x16_bf16 a[16:31], v[64:67], v[44:47], a[16:31]
	ds_read_b128 v[90:93], v81 offset:0x8800
	s_waitcnt vmcnt(10)
	ds_write_b128 v84, v[110:113] offset:0x1000
	v_mfma_f32_32x32x16_bf16 a[0:15], v[64:67], v[48:51], a[0:15]
	ds_read_b128 v[94:97], v81 offset:0x9000
	s_waitcnt vmcnt(9)
	ds_write_b128 v84, v[114:117] offset:0x2000
	s_waitcnt lgkmcnt(5)
	v_mfma_f32_32x32x16_bf16 a[32:47], v[86:89], v[40:43], a[32:47]
	ds_read_b128 v[132:135], v81 offset:0x9800
	s_waitcnt vmcnt(8)
	ds_write_b128 v84, v[118:121] offset:0x3000
	v_mfma_f32_32x32x16_bf16 a[48:63], v[86:89], v[128:131], a[48:63]
	s_waitcnt vmcnt(7)
	ds_write_b128 v84, v[122:125] offset:0x4000
	s_waitcnt lgkmcnt(6)
	v_mfma_f32_32x32x16_bf16 a[64:79], v[90:93], v[40:43], a[64:79]
	s_waitcnt vmcnt(6)
	ds_write_b128 v84, v[140:143] offset:0x5000
	v_mfma_f32_32x32x16_bf16 a[80:95], v[90:93], v[128:131], a[80:95]
	s_waitcnt lgkmcnt(0)
	s_barrier
	s_mov_b32 s4, s5

.LBB0_161:
	s_abs_i32 s2, s0
	v_readlane_b32 s3, v254, 44
	s_mul_hi_u32 s3, s2, s3
	v_readlane_b32 s6, v254, 43
	s_mul_i32 s4, s3, s6
	s_sub_i32 s2, s2, s4
	s_ashr_i32 s1, s0, 31
	s_add_i32 s4, s3, 1
	s_sub_i32 s5, s2, s6
	s_cmp_ge_u32 s2, s6
	s_cselect_b32 s3, s4, s3
	s_cselect_b32 s2, s5, s2
	s_add_i32 s4, s3, 1
	s_cmp_ge_u32 s2, s6
	s_cselect_b32 s2, s4, s3
	s_xor_b32 s2, s2, s1
	s_sub_i32 s1, s2, s1
	s_lshr_b32 s2, s0, 31
	s_add_i32 s2, s0, s2
	s_ashr_i32 s3, s2, 1
	s_abs_i32 s3, s3
	v_readlane_b32 s5, v254, 46
	s_mul_hi_u32 s5, s3, s5
	v_readlane_b32 s6, v254, 45
	s_mul_i32 s5, s5, s6
	s_and_b32 s4, s2, 0xfffffe
	s_sub_i32 s3, s3, s5
	s_sub_i32 s4, s0, s4
	s_ashr_i32 s2, s2, 31
	s_sub_i32 s5, s3, s6
	s_cmp_ge_u32 s3, s6
	s_cselect_b32 s3, s5, s3
	s_sub_i32 s5, s3, s6
	s_cmp_ge_u32 s3, s6
	s_cselect_b32 s3, s5, s3
	s_xor_b32 s3, s3, s2
	s_sub_i32 s2, s3, s2
	v_readlane_b32 s3, v254, 39
	s_add_i32 s2, s3, s2
	s_lshl_b32 s1, s1, 9
	s_lshl_b32 s3, s4, 8
	s_waitcnt vmcnt(2)
	v_mov_b32_e32 v160, v208
	s_add_i32 s1, s1, s3
	v_readlane_b32 s4, v253, 30
	v_ashrrev_i32_e32 v4, 2, v160
	v_add_u32_e32 v0, s1, v4
	v_ashrrev_i32_e32 v1, 31, v0
	v_lshlrev_b64 v[0:1], 11, v[0:1]
	v_readlane_b32 s5, v253, 31
	v_lshlrev_b32_e32 v5, 4, v160
	s_mulk_i32 s2, 0xc0
	v_lshl_add_u64 v[0:1], s[4:5], 0, v[0:1]
	v_and_b32_e32 v192, 48, v5
	v_lshl_add_u64 v[96:97], v[0:1], 0, v[192:193]
	v_add_u32_e32 v0, s2, v4
	v_ashrrev_i32_e32 v1, 31, v0
	v_readlane_b32 s4, v253, 16
	s_mov_b32 s3, 0x20000
	v_lshlrev_b64 v[0:1], 11, v[0:1]
	v_readlane_b32 s5, v253, 17
	v_add_co_u32_e32 v8, vcc, s3, v96
	s_nop 0
	v_lshl_add_u64 v[0:1], s[4:5], 0, v[0:1]
	v_addc_co_u32_e32 v9, vcc, 0, v97, vcc
	s_mov_b32 s4, 0x40000
	v_add_co_u32_e32 v12, vcc, s4, v96
	v_lshl_add_u64 v[98:99], v[0:1], 0, v[192:193]
	s_nop 0
	v_addc_co_u32_e32 v13, vcc, 0, v97, vcc
	v_add_co_u32_e32 v16, vcc, s75, v96
	v_bfe_u32 v6, v160, 5, 1
	s_nop 0
	v_addc_co_u32_e32 v17, vcc, 0, v97, vcc
	v_lshrrev_b32_e32 v7, 2, v160
	v_bfe_u32 v10, v160, 2, 2
	v_add_co_u32_e32 v24, vcc, s3, v98
	v_lshlrev_b32_e32 v11, 1, v160
	v_bitop3_b32 v7, v6, v7, 3 bitop3:0x78
	v_bitop3_b32 v6, v6, v10, 2 bitop3:0x36
	v_and_b32_e32 v10, 0xffffffe0, v4
	v_addc_co_u32_e32 v25, vcc, 0, v99, vcc
	v_and_b32_e32 v161, 31, v160
	s_waitcnt vmcnt(1)
	v_and_b32_e32 v162, 0x80, v11
	v_lshl_add_u32 v163, v10, 1, v10
	v_add_co_u32_e32 v28, vcc, s4, v98
	v_or_b32_e32 v11, v162, v161
	v_or_b32_e32 v10, v163, v161
	global_load_dwordx4 v[0:3], v[96:97], off
	global_load_dwordx4 v[32:35], v[8:9], off
	global_load_dwordx4 v[36:39], v[12:13], off
	global_load_dwordx4 v[40:43], v[16:17], off
	global_load_dwordx4 v[44:47], v[98:99], off
	v_addc_co_u32_e32 v29, vcc, 0, v99, vcc
	v_bitop3_b32 v5, v5, 48, v160 bitop3:0x48
	v_lshlrev_b32_e32 v11, 6, v11
	v_lshlrev_b32_e32 v7, 4, v7
	v_lshlrev_b32_e32 v6, 4, v6
	v_lshl_add_u32 v10, v10, 6, v214
	global_load_dwordx4 v[48:51], v[24:25], off
	global_load_dwordx4 v[52:55], v[28:29], off
	v_or_b32_e32 v110, v11, v7
	v_or_b32_e32 v111, v11, v6
	v_or_b32_e32 v116, v10, v7
	v_or_b32_e32 v117, v10, v6
	v_lshl_or_b32 v118, v4, 6, v5
	global_load_dwordx4 v[4:7], v[96:97], off offset:64
	s_nop 0
	global_load_dwordx4 v[8:11], v[8:9], off offset:64
	s_nop 0
	global_load_dwordx4 v[12:15], v[12:13], off offset:64
	s_nop 0
	global_load_dwordx4 v[16:19], v[16:17], off offset:64
	s_nop 0
	global_load_dwordx4 v[20:23], v[98:99], off offset:64
	s_nop 0
	global_load_dwordx4 v[24:27], v[24:25], off offset:64
	s_nop 0
	global_load_dwordx4 v[28:31], v[28:29], off offset:64
	v_accvgpr_mov_b32 a193, a192
	v_accvgpr_mov_b32 a194, a192
	v_accvgpr_mov_b32 a195, a192
	v_accvgpr_mov_b32 a196, a192
	v_accvgpr_mov_b32 a197, a192
	v_accvgpr_mov_b32 a198, a192
	v_accvgpr_mov_b32 a199, a192
	v_accvgpr_mov_b32 a200, a192
	v_accvgpr_mov_b32 a201, a192
	v_accvgpr_mov_b32 a202, a192
	v_accvgpr_mov_b32 a203, a192
	v_accvgpr_mov_b32 a204, a192
	v_accvgpr_mov_b32 a205, a192
	v_accvgpr_mov_b32 a206, a192
	v_accvgpr_mov_b32 a207, a192


	s_waitcnt vmcnt(13)
	ds_write_b128 v118, v[0:3] offset:0
	s_waitcnt vmcnt(12)
	ds_write_b128 v118, v[32:35] offset:0x1000
	s_waitcnt vmcnt(11)
	ds_write_b128 v118, v[36:39] offset:0x2000
	s_mov_b64 s[8:9], 0x20000
	s_mov_b64 s[6:7], 0x40000
	s_mov_b64 s[10:11], 0x60000
	s_waitcnt vmcnt(10)
	ds_write_b128 v118, v[40:43] offset:0x3000
	s_waitcnt vmcnt(9)
	ds_write_b128 v118, v[44:47] offset:0x4000
	s_waitcnt vmcnt(8)
	ds_write_b128 v118, v[48:51] offset:0x5000
	s_waitcnt vmcnt(7)
	ds_write_b128 v118, v[52:55] offset:0x6000
	s_waitcnt lgkmcnt(0)
	v_mov_b32_e32 v0, 0
	v_lshl_add_u64 v[100:101], v[96:97], 0, s[8:9]
	s_mov_b32 s4, 0
	v_lshl_add_u64 v[102:103], v[96:97], 0, s[6:7]
	v_lshl_add_u64 v[104:105], v[96:97], 0, s[10:11]
	v_lshl_add_u64 v[106:107], v[98:99], 0, s[8:9]
	v_lshl_add_u64 v[108:109], v[98:99], 0, s[6:7]
	s_mov_b32 s3, -2
	v_mov_b32_e32 v1, v0
	v_mov_b32_e32 v2, v0
	v_mov_b32_e32 v3, v0
	v_mov_b32_e32 v128, v0
	v_mov_b32_e32 v129, v0
	v_mov_b32_e32 v130, v0
	v_mov_b32_e32 v131, v0
	v_mov_b32_e32 v32, v0
	v_mov_b32_e32 v33, v0
	v_mov_b32_e32 v34, v0
	v_mov_b32_e32 v35, v0
	s_barrier
.LBB0_162:
	v_readfirstlane_b32 s8, v96
	v_readfirstlane_b32 s9, v97
	v_readfirstlane_b32 s10, v100
	v_readfirstlane_b32 s11, v101
	v_readfirstlane_b32 s12, v102
	v_readfirstlane_b32 s13, v103
	v_readfirstlane_b32 s14, v104
	v_readfirstlane_b32 s15, v105
	v_readfirstlane_b32 s16, v98
	v_readfirstlane_b32 s17, v99
	v_readfirstlane_b32 s18, v106
	v_readfirstlane_b32 s19, v107
	v_readfirstlane_b32 s20, v108
	v_readfirstlane_b32 s21, v109
	v_subrev_u32_e32 v140, s8, v96
	v_subrev_u32_e32 v141, s16, v98
	s_nop 4
	s_add_i32 s5, s4, 64
	s_min_u32 s6, s5, 0x3e0
	s_lshl_b32 s78, s6, 1
	ds_read_b128 v[44:47], v116 offset:0
	ds_read_b128 v[40:43], v116 offset:0x800
	ds_read_b128 v[36:39], v116 offset:0x1000
	ds_read_b128 v[92:95], v110 offset:0
	ds_read_b128 v[88:91], v110 offset:0x800
	ds_read_b128 v[84:87], v110 offset:0x1000
	v_add_u32_e32 v142, s78, v140
	v_add_u32_e32 v143, s78, v141
	global_load_dwordx4 v[56:59], v142, s[8:9]
	ds_read_b128 v[48:51], v110 offset:0x1800
	global_load_dwordx4 v[52:55], v142, s[10:11]
	global_load_dwordx4 v[64:67], v142, s[12:13]
	global_load_dwordx4 v[60:63], v142, s[14:15]
	global_load_dwordx4 v[76:79], v143, s[16:17]
	s_waitcnt lgkmcnt(3)
	v_mfma_f32_32x32x16_bf16 a[80:95], v[92:95], v[44:47], 0
	ds_read_b128 v[80:83], v117 offset:0
	v_mfma_f32_32x32x16_bf16 a[48:63], v[92:95], v[40:43], 0
	global_load_dwordx4 v[68:71], v143, s[18:19]
	v_mfma_f32_32x32x16_bf16 a[64:79], v[92:95], v[36:39], 0
	ds_read_b128 v[112:115], v117 offset:0x800
	s_waitcnt lgkmcnt(4)
	v_mfma_f32_32x32x16_bf16 a[96:111], v[88:91], v[44:47], 0
	global_load_dwordx4 v[72:75], v143, s[20:21]
	v_mfma_f32_32x32x16_bf16 a[112:127], v[88:91], v[40:43], 0
	ds_read_b128 v[120:123], v117 offset:0x1000
	v_mfma_f32_32x32x16_bf16 a[128:143], v[88:91], v[36:39], 0
	ds_read_b128 v[124:127], v111 offset:0
	s_waitcnt lgkmcnt(5)
	v_mfma_f32_32x32x16_bf16 a[144:159], v[84:87], v[44:47], 0
	ds_read_b128 v[128:131], v111 offset:0x800
	s_min_u32 s4, s4, 0x380
	s_lshl_b32 s78, s4, 1
	v_mfma_f32_32x32x16_bf16 a[160:175], v[84:87], v[40:43], 0
	ds_read_b128 v[132:135], v111 offset:0x1000
	s_add_i32 s6, s78, 0xc0
	s_mov_b32 s7, s79
	v_mfma_f32_32x32x16_bf16 a[176:191], v[84:87], v[36:39], 0
	ds_read_b128 v[136:139], v111 offset:0x1800
	s_add_i32 s3, s3, 2
	s_cmp_lt_u32 s3, 30
	s_waitcnt lgkmcnt(7)
	v_mfma_f32_32x32x16_bf16 a[32:47], v[48:51], v[44:47], 0
	s_waitcnt vmcnt(13)
	ds_write_b128 v118, v[4:7] offset:0x8000
	v_mfma_f32_32x32x16_bf16 a[16:31], v[48:51], v[40:43], 0
	s_waitcnt vmcnt(12)
	ds_write_b128 v118, v[8:11] offset:0x9000
	v_mfma_f32_32x32x16_bf16 a[0:15], v[48:51], v[36:39], 0
	s_waitcnt vmcnt(11)
	ds_write_b128 v118, v[12:15] offset:0xa000
	s_waitcnt lgkmcnt(6)
	v_mfma_f32_32x32x16_bf16 a[80:95], v[124:127], v[80:83], a[80:95]
	s_waitcnt vmcnt(10)
	ds_write_b128 v118, v[16:19] offset:0xb000
	v_mfma_f32_32x32x16_bf16 a[48:63], v[124:127], v[112:115], a[48:63]
	s_waitcnt vmcnt(9)
	ds_write_b128 v118, v[20:23] offset:0xc000
	v_mfma_f32_32x32x16_bf16 a[64:79], v[124:127], v[120:123], a[64:79]
	s_waitcnt vmcnt(8)
	ds_write_b128 v118, v[24:27] offset:0xd000
	s_waitcnt lgkmcnt(8)
	v_mfma_f32_32x32x16_bf16 a[96:111], v[128:131], v[80:83], a[96:111]
	s_waitcnt vmcnt(7)
	ds_write_b128 v118, v[28:31] offset:0xe000
	v_mfma_f32_32x32x16_bf16 a[112:127], v[128:131], v[112:115], a[112:127]
	v_mfma_f32_32x32x16_bf16 a[128:143], v[128:131], v[120:123], a[128:143]
	s_waitcnt lgkmcnt(0)
	s_barrier
	ds_read_b128 v[36:39], v116 offset:0x8000
	ds_read_b128 v[40:43], v116 offset:0x8800
	ds_read_b128 v[44:47], v116 offset:0x9000
	ds_read_b128 v[48:51], v110 offset:0x8000
	v_mfma_f32_32x32x16_bf16 a[144:159], v[132:135], v[80:83], a[144:159]
	ds_read_b128 v[84:87], v110 offset:0x8800
	v_mfma_f32_32x32x16_bf16 a[160:175], v[132:135], v[112:115], a[160:175]
	ds_read_b128 v[88:91], v110 offset:0x9000
	v_add_u32_e32 v142, s6, v140
	v_add_u32_e32 v143, s6, v141
	global_load_dwordx4 v[4:7], v142, s[8:9]
	v_mfma_f32_32x32x16_bf16 a[176:191], v[132:135], v[120:123], a[176:191]
	ds_read_b128 v[92:95], v110 offset:0x9800
	global_load_dwordx4 v[8:11], v142, s[10:11]
	v_mfma_f32_32x32x16_bf16 a[32:47], v[136:139], v[80:83], a[32:47]
	global_load_dwordx4 v[12:15], v142, s[12:13]
	v_mfma_f32_32x32x16_bf16 a[16:31], v[136:139], v[112:115], a[16:31]
	global_load_dwordx4 v[16:19], v142, s[14:15]
	v_mfma_f32_32x32x16_bf16 a[0:15], v[136:139], v[120:123], a[0:15]
	global_load_dwordx4 v[20:23], v143, s[16:17]
	s_waitcnt lgkmcnt(3)
	v_mfma_f32_32x32x16_bf16 a[80:95], v[48:51], v[36:39], a[80:95]
	ds_read_b128 v[80:83], v117 offset:0x8000
	v_mfma_f32_32x32x16_bf16 a[48:63], v[48:51], v[40:43], a[48:63]
	global_load_dwordx4 v[24:27], v143, s[18:19]
	v_mfma_f32_32x32x16_bf16 a[64:79], v[48:51], v[44:47], a[64:79]
	ds_read_b128 v[112:115], v117 offset:0x8800
	s_waitcnt lgkmcnt(4)
	v_mfma_f32_32x32x16_bf16 a[96:111], v[84:87], v[36:39], a[96:111]
	global_load_dwordx4 v[28:31], v143, s[20:21]
	v_mfma_f32_32x32x16_bf16 a[112:127], v[84:87], v[40:43], a[112:127]
	ds_read_b128 v[128:131], v117 offset:0x9000
	v_mfma_f32_32x32x16_bf16 a[128:143], v[84:87], v[44:47], a[128:143]
	ds_read_b128 v[120:123], v111 offset:0x8000
	s_waitcnt lgkmcnt(5)
	v_mfma_f32_32x32x16_bf16 a[144:159], v[88:91], v[36:39], a[144:159]
	ds_read_b128 v[124:127], v111 offset:0x8800
	v_mfma_f32_32x32x16_bf16 a[160:175], v[88:91], v[40:43], a[160:175]
	ds_read_b128 v[136:139], v111 offset:0x9000
	v_mfma_f32_32x32x16_bf16 a[176:191], v[88:91], v[44:47], a[176:191]
	ds_read_b128 v[132:135], v111 offset:0x9800
	s_waitcnt lgkmcnt(7)
	v_mfma_f32_32x32x16_bf16 a[32:47], v[92:95], v[36:39], a[32:47]
	s_waitcnt vmcnt(13)
	ds_write_b128 v118, v[56:59] offset:0
	v_mfma_f32_32x32x16_bf16 a[16:31], v[92:95], v[40:43], a[16:31]
	s_waitcnt vmcnt(12)
	ds_write_b128 v118, v[52:55] offset:0x1000
	v_mfma_f32_32x32x16_bf16 a[0:15], v[92:95], v[44:47], a[0:15]
	s_waitcnt vmcnt(11)
	ds_write_b128 v118, v[64:67] offset:0x2000
	s_waitcnt lgkmcnt(6)
	v_mfma_f32_32x32x16_bf16 a[80:95], v[120:123], v[80:83], a[80:95]
	s_waitcnt vmcnt(10)
	ds_write_b128 v118, v[60:63] offset:0x3000
	v_mfma_f32_32x32x16_bf16 a[48:63], v[120:123], v[112:115], a[48:63]
	s_waitcnt vmcnt(9)
	ds_write_b128 v118, v[76:79] offset:0x4000
	v_mfma_f32_32x32x16_bf16 a[64:79], v[120:123], v[128:131], a[64:79]
	s_waitcnt vmcnt(8)
	ds_write_b128 v118, v[68:71] offset:0x5000
	s_waitcnt lgkmcnt(8)
	v_mfma_f32_32x32x16_bf16 a[96:111], v[124:127], v[80:83], a[96:111]
	s_waitcnt vmcnt(7)
	ds_write_b128 v118, v[72:75] offset:0x6000
	v_mfma_f32_32x32x16_bf16 a[112:127], v[124:127], v[112:115], a[112:127]
	v_mfma_f32_32x32x16_bf16 a[128:143], v[124:127], v[128:131], a[128:143]
	s_waitcnt lgkmcnt(0)
	s_barrier
	s_mov_b32 s4, s5

.LBB0_204:
	s_abs_i32 s4, s0
	v_readlane_b32 s5, v254, 51
	s_mul_hi_u32 s5, s4, s5
	s_mul_i32 s6, s5, s8
	s_sub_i32 s4, s4, s6
	s_ashr_i32 s1, s0, 31
	s_add_i32 s6, s5, 1
	s_sub_i32 s7, s4, s8
	s_cmp_ge_u32 s4, s8
	s_cselect_b32 s5, s6, s5
	s_cselect_b32 s4, s7, s4
	s_add_i32 s6, s5, 1
	s_cmp_ge_u32 s4, s8
	s_cselect_b32 s4, s6, s5
	s_xor_b32 s4, s4, s1
	s_sub_i32 s4, s4, s1
	s_lshr_b32 s1, s1, 30
	s_add_i32 s1, s0, s1
	s_ashr_i32 s5, s1, 2
	s_abs_i32 s5, s5
	v_readlane_b32 s7, v254, 53
	s_mul_hi_u32 s7, s5, s7
	v_readlane_b32 s8, v254, 52
	s_mul_i32 s7, s7, s8
	s_and_b32 s6, s1, 0xfffffc
	s_sub_i32 s5, s5, s7
	s_sub_i32 s6, s0, s6
	s_ashr_i32 s1, s1, 31
	s_sub_i32 s7, s5, s8
	s_cmp_ge_u32 s5, s8
	s_cselect_b32 s5, s7, s5
	s_sub_i32 s7, s5, s8
	s_cmp_ge_u32 s5, s8
	s_cselect_b32 s5, s7, s5
	s_xor_b32 s5, s5, s1
	s_sub_i32 s1, s5, s1
	v_readlane_b32 s5, v254, 47
	s_add_i32 s5, s5, s1
	s_lshl_b32 s1, s4, 10
	s_lshl_b32 s4, s6, 8
	v_mov_b32_e32 v203, v208
	s_add_i32 s1, s1, s4
	v_readlane_b32 s6, v253, 34
	v_ashrrev_i32_e32 v4, 2, v203
	v_add_u32_e32 v0, s1, v4
	v_ashrrev_i32_e32 v1, 31, v0
	v_lshlrev_b64 v[0:1], 11, v[0:1]
	v_readlane_b32 s7, v253, 35
	v_lshlrev_b32_e32 v5, 4, v203
	s_mul_i32 s4, s5, 0xc0
	v_lshl_add_u64 v[0:1], s[6:7], 0, v[0:1]
	v_and_b32_e32 v192, 48, v5
	v_lshl_add_u64 v[100:101], v[0:1], 0, v[192:193]
	v_add_u32_e32 v0, s4, v4
	v_ashrrev_i32_e32 v1, 31, v0
	v_readlane_b32 s6, v253, 61
	s_mov_b32 s5, 0x20000
	v_lshlrev_b64 v[0:1], 11, v[0:1]
	v_readlane_b32 s7, v253, 62
	v_add_co_u32_e32 v8, vcc, s5, v100
	s_nop 0
	v_lshl_add_u64 v[0:1], s[6:7], 0, v[0:1]
	v_addc_co_u32_e32 v9, vcc, 0, v101, vcc
	s_mov_b32 s6, 0x40000
	v_add_co_u32_e32 v12, vcc, s6, v100
	v_lshl_add_u64 v[102:103], v[0:1], 0, v[192:193]
	s_nop 0
	v_addc_co_u32_e32 v13, vcc, 0, v101, vcc
	v_add_co_u32_e32 v16, vcc, s75, v100
	v_bfe_u32 v6, v203, 5, 1
	s_nop 0
	v_addc_co_u32_e32 v17, vcc, 0, v101, vcc
	v_lshrrev_b32_e32 v7, 2, v203
	v_bfe_u32 v10, v203, 2, 2
	v_add_co_u32_e32 v24, vcc, s5, v102
	v_lshlrev_b32_e32 v11, 1, v203
	v_bitop3_b32 v7, v6, v7, 3 bitop3:0x78
	v_bitop3_b32 v6, v6, v10, 2 bitop3:0x36
	v_and_b32_e32 v10, 0xffffffe0, v4
	v_addc_co_u32_e32 v25, vcc, 0, v103, vcc
	v_and_b32_e32 v192, 31, v203
	v_and_b32_e32 v204, 0x80, v11
	v_lshl_add_u32 v205, v10, 1, v10
	v_add_co_u32_e32 v28, vcc, s6, v102
	v_or_b32_e32 v11, v204, v192
	v_or_b32_e32 v10, v205, v192
	global_load_dwordx4 v[0:3], v[100:101], off
	global_load_dwordx4 v[32:35], v[8:9], off
	global_load_dwordx4 v[36:39], v[12:13], off
	global_load_dwordx4 v[40:43], v[16:17], off
	global_load_dwordx4 v[44:47], v[102:103], off
	v_addc_co_u32_e32 v29, vcc, 0, v103, vcc
	v_bitop3_b32 v5, v5, 48, v203 bitop3:0x48
	v_lshlrev_b32_e32 v11, 6, v11
	v_lshlrev_b32_e32 v7, 4, v7
	v_lshlrev_b32_e32 v6, 4, v6
	v_lshl_add_u32 v10, v10, 6, v214
	global_load_dwordx4 v[48:51], v[24:25], off
	global_load_dwordx4 v[52:55], v[28:29], off
	v_or_b32_e32 v114, v11, v7
	v_or_b32_e32 v115, v11, v6
	v_or_b32_e32 v116, v10, v7
	v_or_b32_e32 v117, v10, v6
	v_lshl_or_b32 v118, v4, 6, v5
	global_load_dwordx4 v[4:7], v[100:101], off offset:64
	s_nop 0
	global_load_dwordx4 v[8:11], v[8:9], off offset:64
	s_nop 0
	global_load_dwordx4 v[12:15], v[12:13], off offset:64
	s_nop 0
	global_load_dwordx4 v[16:19], v[16:17], off offset:64
	s_nop 0
	global_load_dwordx4 v[20:23], v[102:103], off offset:64
	s_nop 0
	global_load_dwordx4 v[24:27], v[24:25], off offset:64
	s_nop 0
	global_load_dwordx4 v[28:31], v[28:29], off offset:64
	v_accvgpr_mov_b32 a193, a192
	v_accvgpr_mov_b32 a194, a192
	v_accvgpr_mov_b32 a195, a192
	v_accvgpr_mov_b32 a196, a192
	v_accvgpr_mov_b32 a197, a192
	v_accvgpr_mov_b32 a198, a192
	v_accvgpr_mov_b32 a199, a192
	v_accvgpr_mov_b32 a200, a192
	v_accvgpr_mov_b32 a201, a192
	v_accvgpr_mov_b32 a202, a192
	v_accvgpr_mov_b32 a203, a192
	v_accvgpr_mov_b32 a204, a192
	v_accvgpr_mov_b32 a205, a192
	v_accvgpr_mov_b32 a206, a192
	v_accvgpr_mov_b32 a207, a192


	s_waitcnt vmcnt(13)
	ds_write_b128 v118, v[0:3] offset:0
	s_waitcnt vmcnt(12)
	ds_write_b128 v118, v[32:35] offset:0x1000
	s_waitcnt vmcnt(11)
	ds_write_b128 v118, v[36:39] offset:0x2000
	s_mov_b64 s[10:11], 0x20000
	s_mov_b64 s[8:9], 0x40000
	s_mov_b64 s[12:13], 0x60000
	v_mov_b32_e32 v0, 0
	s_waitcnt vmcnt(10)
	ds_write_b128 v118, v[40:43] offset:0x3000
	s_waitcnt vmcnt(9)
	ds_write_b128 v118, v[44:47] offset:0x4000
	s_waitcnt vmcnt(8)
	ds_write_b128 v118, v[48:51] offset:0x5000
	s_waitcnt vmcnt(7)
	ds_write_b128 v118, v[52:55] offset:0x6000
	s_waitcnt lgkmcnt(0)
	v_lshl_add_u64 v[104:105], v[100:101], 0, s[10:11]
	s_mov_b32 s6, 0
	v_lshl_add_u64 v[106:107], v[100:101], 0, s[8:9]
	v_lshl_add_u64 v[108:109], v[100:101], 0, s[12:13]
	v_lshl_add_u64 v[110:111], v[102:103], 0, s[10:11]
	v_lshl_add_u64 v[112:113], v[102:103], 0, s[8:9]
	s_mov_b32 s5, -2
	v_mov_b32_e32 v1, v0
	v_mov_b32_e32 v2, v0
	v_mov_b32_e32 v3, v0
	v_mov_b32_e32 v194, v0
	v_mov_b32_e32 v195, v0
	v_mov_b32_e32 v196, v0
	v_mov_b32_e32 v197, v0
	v_mov_b32_e32 v32, v0
	v_mov_b32_e32 v33, v0
	v_mov_b32_e32 v34, v0
	v_mov_b32_e32 v35, v0
	s_barrier
.LBB0_205:
	v_readfirstlane_b32 s10, v100
	v_readfirstlane_b32 s11, v101
	v_readfirstlane_b32 s12, v104
	v_readfirstlane_b32 s13, v105
	v_readfirstlane_b32 s14, v106
	v_readfirstlane_b32 s15, v107
	v_readfirstlane_b32 s16, v108
	v_readfirstlane_b32 s17, v109
	v_readfirstlane_b32 s18, v102
	v_readfirstlane_b32 s19, v103
	v_readfirstlane_b32 s20, v110
	v_readfirstlane_b32 s21, v111
	v_readfirstlane_b32 s22, v112
	v_readfirstlane_b32 s23, v113
	v_subrev_u32_e32 v140, s10, v100
	v_subrev_u32_e32 v141, s18, v102
	s_nop 4
	s_add_i32 s7, s6, 64
	s_min_u32 s8, s7, 0x3e0
	s_lshl_b32 s78, s8, 1
	ds_read_b128 v[52:55], v116 offset:0
	ds_read_b128 v[48:51], v116 offset:0x800
	ds_read_b128 v[44:47], v116 offset:0x1000
	ds_read_b128 v[96:99], v114 offset:0
	ds_read_b128 v[92:95], v114 offset:0x800
	ds_read_b128 v[88:91], v114 offset:0x1000
	v_add_u32_e32 v142, s78, v140
	v_add_u32_e32 v143, s78, v141
	global_load_dwordx4 v[64:67], v142, s[10:11]
	ds_read_b128 v[56:59], v114 offset:0x1800
	global_load_dwordx4 v[60:63], v142, s[12:13]
	global_load_dwordx4 v[72:75], v142, s[14:15]
	global_load_dwordx4 v[68:71], v142, s[16:17]
	global_load_dwordx4 v[84:87], v143, s[18:19]
	s_waitcnt lgkmcnt(3)
	v_mfma_f32_32x32x16_bf16 a[48:63], v[96:99], v[52:55], 0
	ds_read_b128 v[36:39], v117 offset:0
	v_mfma_f32_32x32x16_bf16 a[64:79], v[96:99], v[48:51], 0
	global_load_dwordx4 v[76:79], v143, s[20:21]
	v_mfma_f32_32x32x16_bf16 a[80:95], v[96:99], v[44:47], 0
	ds_read_b128 v[40:43], v117 offset:0x800
	s_waitcnt lgkmcnt(4)
	v_mfma_f32_32x32x16_bf16 a[96:111], v[92:95], v[52:55], 0
	global_load_dwordx4 v[80:83], v143, s[22:23]
	v_mfma_f32_32x32x16_bf16 a[112:127], v[92:95], v[48:51], 0
	ds_read_b128 v[120:123], v117 offset:0x1000
	v_mfma_f32_32x32x16_bf16 a[128:143], v[92:95], v[44:47], 0
	ds_read_b128 v[124:127], v115 offset:0
	s_waitcnt lgkmcnt(5)
	v_mfma_f32_32x32x16_bf16 a[144:159], v[88:91], v[52:55], 0
	ds_read_b128 v[128:131], v115 offset:0x800
	s_min_u32 s6, s6, 0x380
	s_lshl_b32 s78, s6, 1
	v_mfma_f32_32x32x16_bf16 a[160:175], v[88:91], v[48:51], 0
	ds_read_b128 v[132:135], v115 offset:0x1000
	s_add_i32 s8, s78, 0xc0
	s_mov_b32 s9, s79
	v_mfma_f32_32x32x16_bf16 a[176:191], v[88:91], v[44:47], 0
	ds_read_b128 v[136:139], v115 offset:0x1800
	s_add_i32 s5, s5, 2
	s_cmp_lt_u32 s5, 30
	s_waitcnt lgkmcnt(7)
	v_mfma_f32_32x32x16_bf16 a[32:47], v[56:59], v[52:55], 0
	s_waitcnt vmcnt(13)
	ds_write_b128 v118, v[4:7] offset:0x8000
	v_mfma_f32_32x32x16_bf16 a[16:31], v[56:59], v[48:51], 0
	s_waitcnt vmcnt(12)
	ds_write_b128 v118, v[8:11] offset:0x9000
	v_mfma_f32_32x32x16_bf16 a[0:15], v[56:59], v[44:47], 0
	s_waitcnt vmcnt(11)
	ds_write_b128 v118, v[12:15] offset:0xa000
	s_waitcnt lgkmcnt(6)
	v_mfma_f32_32x32x16_bf16 a[48:63], v[124:127], v[36:39], a[48:63]
	s_waitcnt vmcnt(10)
	ds_write_b128 v118, v[16:19] offset:0xb000
	v_mfma_f32_32x32x16_bf16 a[64:79], v[124:127], v[40:43], a[64:79]
	s_waitcnt vmcnt(9)
	ds_write_b128 v118, v[20:23] offset:0xc000
	v_mfma_f32_32x32x16_bf16 a[80:95], v[124:127], v[120:123], a[80:95]
	s_waitcnt vmcnt(8)
	ds_write_b128 v118, v[24:27] offset:0xd000
	s_waitcnt lgkmcnt(8)
	v_mfma_f32_32x32x16_bf16 a[96:111], v[128:131], v[36:39], a[96:111]
	s_waitcnt vmcnt(7)
	ds_write_b128 v118, v[28:31] offset:0xe000
	v_mfma_f32_32x32x16_bf16 a[112:127], v[128:131], v[40:43], a[112:127]
	v_mfma_f32_32x32x16_bf16 a[128:143], v[128:131], v[120:123], a[128:143]
	s_waitcnt lgkmcnt(0)
	s_barrier
	ds_read_b128 v[44:47], v116 offset:0x8000
	ds_read_b128 v[48:51], v116 offset:0x8800
	ds_read_b128 v[52:55], v116 offset:0x9000
	ds_read_b128 v[56:59], v114 offset:0x8000
	v_mfma_f32_32x32x16_bf16 a[144:159], v[132:135], v[36:39], a[144:159]
	ds_read_b128 v[88:91], v114 offset:0x8800
	v_mfma_f32_32x32x16_bf16 a[160:175], v[132:135], v[40:43], a[160:175]
	ds_read_b128 v[92:95], v114 offset:0x9000
	v_add_u32_e32 v142, s8, v140
	v_add_u32_e32 v143, s8, v141
	global_load_dwordx4 v[4:7], v142, s[10:11]
	v_mfma_f32_32x32x16_bf16 a[176:191], v[132:135], v[120:123], a[176:191]
	ds_read_b128 v[96:99], v114 offset:0x9800
	global_load_dwordx4 v[8:11], v142, s[12:13]
	v_mfma_f32_32x32x16_bf16 a[32:47], v[136:139], v[36:39], a[32:47]
	global_load_dwordx4 v[12:15], v142, s[14:15]
	v_mfma_f32_32x32x16_bf16 a[16:31], v[136:139], v[40:43], a[16:31]
	global_load_dwordx4 v[16:19], v142, s[16:17]
	v_mfma_f32_32x32x16_bf16 a[0:15], v[136:139], v[120:123], a[0:15]
	global_load_dwordx4 v[20:23], v143, s[18:19]
	s_waitcnt lgkmcnt(3)
	v_mfma_f32_32x32x16_bf16 a[48:63], v[56:59], v[44:47], a[48:63]
	ds_read_b128 v[40:43], v117 offset:0x8000
	v_mfma_f32_32x32x16_bf16 a[64:79], v[56:59], v[48:51], a[64:79]
	global_load_dwordx4 v[24:27], v143, s[20:21]
	v_mfma_f32_32x32x16_bf16 a[80:95], v[56:59], v[52:55], a[80:95]
	ds_read_b128 v[36:39], v117 offset:0x8800
	s_waitcnt lgkmcnt(4)
	v_mfma_f32_32x32x16_bf16 a[96:111], v[88:91], v[44:47], a[96:111]
	global_load_dwordx4 v[28:31], v143, s[22:23]
	v_mfma_f32_32x32x16_bf16 a[112:127], v[88:91], v[48:51], a[112:127]
	ds_read_b128 v[194:197], v117 offset:0x9000
	v_mfma_f32_32x32x16_bf16 a[128:143], v[88:91], v[52:55], a[128:143]
	ds_read_b128 v[120:123], v115 offset:0x8000
	s_waitcnt lgkmcnt(5)
	v_mfma_f32_32x32x16_bf16 a[144:159], v[92:95], v[44:47], a[144:159]
	ds_read_b128 v[124:127], v115 offset:0x8800
	v_mfma_f32_32x32x16_bf16 a[160:175], v[92:95], v[48:51], a[160:175]
	ds_read_b128 v[128:131], v115 offset:0x9000
	v_mfma_f32_32x32x16_bf16 a[176:191], v[92:95], v[52:55], a[176:191]
	ds_read_b128 v[198:201], v115 offset:0x9800
	s_waitcnt lgkmcnt(7)
	v_mfma_f32_32x32x16_bf16 a[32:47], v[96:99], v[44:47], a[32:47]
	s_waitcnt vmcnt(13)
	ds_write_b128 v118, v[64:67] offset:0
	v_mfma_f32_32x32x16_bf16 a[16:31], v[96:99], v[48:51], a[16:31]
	s_waitcnt vmcnt(12)
	ds_write_b128 v118, v[60:63] offset:0x1000
	v_mfma_f32_32x32x16_bf16 a[0:15], v[96:99], v[52:55], a[0:15]
	s_waitcnt vmcnt(11)
	ds_write_b128 v118, v[72:75] offset:0x2000
	s_waitcnt lgkmcnt(6)
	v_mfma_f32_32x32x16_bf16 a[48:63], v[120:123], v[40:43], a[48:63]
	s_waitcnt vmcnt(10)
	ds_write_b128 v118, v[68:71] offset:0x3000
	v_mfma_f32_32x32x16_bf16 a[64:79], v[120:123], v[36:39], a[64:79]
	s_waitcnt vmcnt(9)
	ds_write_b128 v118, v[84:87] offset:0x4000
	v_mfma_f32_32x32x16_bf16 a[80:95], v[120:123], v[194:197], a[80:95]
	s_waitcnt vmcnt(8)
	ds_write_b128 v118, v[76:79] offset:0x5000
	s_waitcnt lgkmcnt(8)
	v_mfma_f32_32x32x16_bf16 a[96:111], v[124:127], v[40:43], a[96:111]
	s_waitcnt vmcnt(7)
	ds_write_b128 v118, v[80:83] offset:0x6000
	v_mfma_f32_32x32x16_bf16 a[112:127], v[124:127], v[36:39], a[112:127]
	v_mfma_f32_32x32x16_bf16 a[128:143], v[124:127], v[194:197], a[128:143]
	s_waitcnt lgkmcnt(0)
	s_barrier
	s_mov_b32 s6, s7

.LBB0_223:
	s_abs_i32 s2, s0
	v_readlane_b32 s3, v254, 58
	s_mul_hi_u32 s3, s2, s3
	s_mul_i32 s4, s3, s6
	s_sub_i32 s2, s2, s4
	s_ashr_i32 s1, s0, 31
	s_add_i32 s4, s3, 1
	s_sub_i32 s5, s2, s6
	s_cmp_ge_u32 s2, s6
	s_cselect_b32 s3, s4, s3
	s_cselect_b32 s2, s5, s2
	s_add_i32 s4, s3, 1
	s_cmp_ge_u32 s2, s6
	s_cselect_b32 s2, s4, s3
	s_xor_b32 s2, s2, s1
	s_sub_i32 s2, s2, s1
	s_lshr_b32 s1, s1, 30
	s_add_i32 s1, s0, s1
	s_ashr_i32 s3, s1, 2
	s_abs_i32 s3, s3
	v_readlane_b32 s5, v254, 60
	s_mul_hi_u32 s5, s3, s5
	v_readlane_b32 s6, v254, 59
	s_mul_i32 s5, s5, s6
	s_and_b32 s4, s1, 0xfffffc
	s_sub_i32 s3, s3, s5
	s_sub_i32 s4, s0, s4
	s_ashr_i32 s1, s1, 31
	s_sub_i32 s5, s3, s6
	s_cmp_ge_u32 s3, s6
	s_cselect_b32 s3, s5, s3
	s_sub_i32 s5, s3, s6
	s_cmp_ge_u32 s3, s6
	s_cselect_b32 s3, s5, s3
	s_xor_b32 s3, s3, s1
	s_sub_i32 s1, s3, s1
	v_readlane_b32 s3, v254, 54
	s_add_i32 s3, s3, s1
	s_lshl_b32 s1, s2, 10
	s_lshl_b32 s2, s4, 8
	v_mov_b32_e32 v136, v208
	s_add_i32 s1, s1, s2
	v_readlane_b32 s4, v253, 34
	v_ashrrev_i32_e32 v4, 2, v136
	v_add_u32_e32 v0, s1, v4
	v_ashrrev_i32_e32 v1, 31, v0
	s_lshl_b32 s2, s3, 7
	v_lshlrev_b64 v[0:1], 11, v[0:1]
	v_readlane_b32 s5, v253, 35
	v_lshlrev_b32_e32 v5, 4, v136
	s_addk_i32 s2, 0x3000
	v_lshl_add_u64 v[0:1], s[4:5], 0, v[0:1]
	v_and_b32_e32 v192, 48, v5
	v_lshl_add_u64 v[68:69], v[0:1], 0, v[192:193]
	v_add_u32_e32 v0, s2, v4
	v_ashrrev_i32_e32 v1, 31, v0
	v_readlane_b32 s4, v253, 61
	s_mov_b32 s3, 0x20000
	v_lshlrev_b64 v[0:1], 11, v[0:1]
	v_readlane_b32 s5, v253, 62
	v_add_co_u32_e32 v8, vcc, s3, v68
	s_nop 0
	v_lshl_add_u64 v[0:1], s[4:5], 0, v[0:1]
	v_addc_co_u32_e32 v9, vcc, 0, v69, vcc
	s_mov_b32 s4, 0x40000
	v_add_co_u32_e32 v12, vcc, s4, v68
	v_bfe_u32 v6, v136, 5, 1
	s_nop 0
	v_addc_co_u32_e32 v13, vcc, 0, v69, vcc
	v_lshrrev_b32_e32 v7, 2, v136
	v_bfe_u32 v10, v136, 2, 2
	v_add_co_u32_e32 v16, vcc, s75, v68
	v_lshlrev_b32_e32 v11, 1, v136
	v_bitop3_b32 v7, v6, v7, 3 bitop3:0x78
	v_bitop3_b32 v6, v6, v10, 2 bitop3:0x36
	v_ashrrev_i32_e32 v10, 1, v136
	v_lshl_add_u64 v[70:71], v[0:1], 0, v[192:193]
	v_addc_co_u32_e32 v17, vcc, 0, v69, vcc
	v_and_b32_e32 v137, 31, v136
	s_waitcnt vmcnt(7)
	v_and_b32_e32 v138, 0x80, v11
	v_and_b32_e32 v139, 0xffffffc0, v10
	v_add_co_u32_e32 v24, vcc, s3, v70
	v_or_b32_e32 v11, v138, v137
	v_or_b32_e32 v10, v139, v137
	global_load_dwordx4 v[0:3], v[68:69], off
	global_load_dwordx4 v[28:31], v[8:9], off
	global_load_dwordx4 v[32:35], v[12:13], off
	global_load_dwordx4 v[36:39], v[16:17], off
	global_load_dwordx4 v[40:43], v[70:71], off
	v_addc_co_u32_e32 v25, vcc, 0, v71, vcc
	v_bitop3_b32 v5, v5, 48, v136 bitop3:0x48
	v_lshlrev_b32_e32 v11, 6, v11
	v_lshlrev_b32_e32 v7, 4, v7
	v_lshlrev_b32_e32 v6, 4, v6
	v_lshl_add_u32 v10, v10, 6, v214
	global_load_dwordx4 v[44:47], v[24:25], off
	v_or_b32_e32 v80, v11, v7
	v_or_b32_e32 v81, v11, v6
	v_or_b32_e32 v82, v10, v7
	v_or_b32_e32 v83, v10, v6
	v_lshl_or_b32 v84, v4, 6, v5
	global_load_dwordx4 v[4:7], v[68:69], off offset:64
	s_nop 0
	global_load_dwordx4 v[8:11], v[8:9], off offset:64
	s_nop 0
	global_load_dwordx4 v[12:15], v[12:13], off offset:64
	s_nop 0
	global_load_dwordx4 v[16:19], v[16:17], off offset:64
	s_nop 0
	global_load_dwordx4 v[20:23], v[70:71], off offset:64
	s_nop 0
	global_load_dwordx4 v[24:27], v[24:25], off offset:64
	v_accvgpr_mov_b32 a193, a192
	v_accvgpr_mov_b32 a194, a192
	v_accvgpr_mov_b32 a195, a192
	v_accvgpr_mov_b32 a196, a192
	v_accvgpr_mov_b32 a197, a192
	v_accvgpr_mov_b32 a198, a192
	v_accvgpr_mov_b32 a199, a192
	v_accvgpr_mov_b32 a200, a192
	v_accvgpr_mov_b32 a201, a192
	v_accvgpr_mov_b32 a202, a192
	v_accvgpr_mov_b32 a203, a192
	v_accvgpr_mov_b32 a204, a192
	v_accvgpr_mov_b32 a205, a192
	v_accvgpr_mov_b32 a206, a192
	v_accvgpr_mov_b32 a207, a192


	s_waitcnt vmcnt(11)
	ds_write_b128 v84, v[0:3] offset:0
	s_waitcnt vmcnt(10)
	ds_write_b128 v84, v[28:31] offset:0x1000
	s_waitcnt vmcnt(9)
	ds_write_b128 v84, v[32:35] offset:0x2000
	s_mov_b64 s[6:7], 0x40000
	s_mov_b64 s[8:9], 0x20000
	v_lshl_add_u64 v[74:75], v[68:69], 0, s[6:7]
	s_mov_b64 s[6:7], 0x60000
	v_mov_b32_e32 v0, 0
	s_waitcnt vmcnt(8)
	ds_write_b128 v84, v[36:39] offset:0x3000
	s_waitcnt vmcnt(7)
	ds_write_b128 v84, v[40:43] offset:0x4000
	s_waitcnt vmcnt(6)
	ds_write_b128 v84, v[44:47] offset:0x5000
	s_waitcnt lgkmcnt(0)
	v_lshl_add_u64 v[72:73], v[68:69], 0, s[8:9]
	s_mov_b32 s4, 0
	v_lshl_add_u64 v[76:77], v[68:69], 0, s[6:7]
	v_lshl_add_u64 v[78:79], v[70:71], 0, s[8:9]
	s_mov_b32 s3, -2
	v_mov_b32_e32 v1, v0
	v_mov_b32_e32 v2, v0
	v_mov_b32_e32 v3, v0
	v_mov_b32_e32 v28, v0
	v_mov_b32_e32 v29, v0
	v_mov_b32_e32 v30, v0
	v_mov_b32_e32 v31, v0
	v_mov_b32_e32 v32, v0
	v_mov_b32_e32 v33, v0
	v_mov_b32_e32 v34, v0
	v_mov_b32_e32 v35, v0
	v_mov_b32_e32 v36, v0
	v_mov_b32_e32 v37, v0
	v_mov_b32_e32 v38, v0
	v_mov_b32_e32 v39, v0
	s_barrier
.LBB0_224:
	v_readfirstlane_b32 s8, v68
	v_readfirstlane_b32 s9, v69
	v_readfirstlane_b32 s10, v72
	v_readfirstlane_b32 s11, v73
	v_readfirstlane_b32 s12, v74
	v_readfirstlane_b32 s13, v75
	v_readfirstlane_b32 s14, v76
	v_readfirstlane_b32 s15, v77
	v_readfirstlane_b32 s16, v70
	v_readfirstlane_b32 s17, v71
	v_readfirstlane_b32 s18, v78
	v_readfirstlane_b32 s19, v79
	v_subrev_u32_e32 v144, s8, v68
	v_subrev_u32_e32 v145, s16, v70
	s_nop 4
	s_add_i32 s5, s4, 64
	s_min_u32 s6, s5, 0x3e0
	s_lshl_b32 s78, s6, 1
	ds_read_b128 v[48:51], v82 offset:0
	ds_read_b128 v[44:47], v82 offset:0x800
	ds_read_b128 v[64:67], v80 offset:0
	ds_read_b128 v[60:63], v80 offset:0x800
	ds_read_b128 v[56:59], v80 offset:0x1000
	v_add_u32_e32 v146, s78, v144
	v_add_u32_e32 v147, s78, v145
	global_load_dwordx4 v[106:109], v146, s[8:9]
	ds_read_b128 v[52:55], v80 offset:0x1800
	global_load_dwordx4 v[110:113], v146, s[10:11]
	global_load_dwordx4 v[114:117], v146, s[12:13]
	s_waitcnt lgkmcnt(3)
	v_mfma_f32_32x32x16_bf16 a[32:47], v[64:67], v[48:51], 0
	ds_read_b128 v[40:43], v83 offset:0
	v_mfma_f32_32x32x16_bf16 a[48:63], v[64:67], v[44:47], 0
	global_load_dwordx4 v[118:121], v146, s[14:15]
	s_waitcnt lgkmcnt(3)
	v_mfma_f32_32x32x16_bf16 a[64:79], v[60:63], v[48:51], 0
	ds_read_b128 v[86:89], v83 offset:0x800
	v_mfma_f32_32x32x16_bf16 a[80:95], v[60:63], v[44:47], 0
	global_load_dwordx4 v[122:125], v147, s[16:17]
	s_waitcnt lgkmcnt(3)
	v_mfma_f32_32x32x16_bf16 a[96:111], v[56:59], v[48:51], 0
	ds_read_b128 v[90:93], v81 offset:0
	v_mfma_f32_32x32x16_bf16 a[112:127], v[56:59], v[44:47], 0
	global_load_dwordx4 v[140:143], v147, s[18:19]
	s_waitcnt vmcnt(11)
	ds_write_b128 v84, v[4:7] offset:0x8000
	s_waitcnt lgkmcnt(4)
	v_mfma_f32_32x32x16_bf16 a[16:31], v[52:55], v[48:51], 0
	ds_read_b128 v[94:97], v81 offset:0x800
	s_min_u32 s4, s4, 0x380
	s_lshl_b32 s78, s4, 1
	s_waitcnt vmcnt(10)
	ds_write_b128 v84, v[8:11] offset:0x9000
	v_mfma_f32_32x32x16_bf16 a[0:15], v[52:55], v[44:47], 0
	ds_read_b128 v[98:101], v81 offset:0x1000
	s_add_i32 s6, s78, 0xc0
	s_mov_b32 s7, s79
	s_waitcnt vmcnt(9)
	ds_write_b128 v84, v[12:15] offset:0xa000
	s_waitcnt lgkmcnt(5)
	v_mfma_f32_32x32x16_bf16 a[32:47], v[90:93], v[40:43], a[32:47]
	ds_read_b128 v[102:105], v81 offset:0x1800
	s_add_i32 s3, s3, 2
	s_cmp_lt_u32 s3, 30
	s_waitcnt vmcnt(8)
	ds_write_b128 v84, v[16:19] offset:0xb000
	v_mfma_f32_32x32x16_bf16 a[48:63], v[90:93], v[86:89], a[48:63]
	s_waitcnt vmcnt(7)
	ds_write_b128 v84, v[20:23] offset:0xc000
	s_waitcnt lgkmcnt(6)
	v_mfma_f32_32x32x16_bf16 a[64:79], v[94:97], v[40:43], a[64:79]
	s_waitcnt vmcnt(6)
	ds_write_b128 v84, v[24:27] offset:0xd000
	v_mfma_f32_32x32x16_bf16 a[80:95], v[94:97], v[86:89], a[80:95]
	s_waitcnt lgkmcnt(0)
	s_barrier
	ds_read_b128 v[44:47], v82 offset:0x8000
	ds_read_b128 v[48:51], v82 offset:0x8800
	ds_read_b128 v[52:55], v80 offset:0x8000
	v_mfma_f32_32x32x16_bf16 a[96:111], v[98:101], v[40:43], a[96:111]
	ds_read_b128 v[56:59], v80 offset:0x8800
	v_mfma_f32_32x32x16_bf16 a[112:127], v[98:101], v[86:89], a[112:127]
	ds_read_b128 v[60:63], v80 offset:0x9000
	v_add_u32_e32 v146, s6, v144
	v_add_u32_e32 v147, s6, v145
	global_load_dwordx4 v[4:7], v146, s[8:9]
	v_mfma_f32_32x32x16_bf16 a[16:31], v[102:105], v[40:43], a[16:31]
	ds_read_b128 v[64:67], v80 offset:0x9800
	global_load_dwordx4 v[8:11], v146, s[10:11]
	v_mfma_f32_32x32x16_bf16 a[0:15], v[102:105], v[86:89], a[0:15]
	global_load_dwordx4 v[12:15], v146, s[12:13]
	s_waitcnt lgkmcnt(3)
	v_mfma_f32_32x32x16_bf16 a[32:47], v[52:55], v[44:47], a[32:47]
	ds_read_b128 v[40:43], v83 offset:0x8000
	v_mfma_f32_32x32x16_bf16 a[48:63], v[52:55], v[48:51], a[48:63]
	global_load_dwordx4 v[16:19], v146, s[14:15]
	s_waitcnt lgkmcnt(3)
	v_mfma_f32_32x32x16_bf16 a[64:79], v[56:59], v[44:47], a[64:79]
	ds_read_b128 v[128:131], v83 offset:0x8800
	v_mfma_f32_32x32x16_bf16 a[80:95], v[56:59], v[48:51], a[80:95]
	global_load_dwordx4 v[20:23], v147, s[16:17]
	s_waitcnt lgkmcnt(3)
	v_mfma_f32_32x32x16_bf16 a[96:111], v[60:63], v[44:47], a[96:111]
	ds_read_b128 v[86:89], v81 offset:0x8000
	v_mfma_f32_32x32x16_bf16 a[112:127], v[60:63], v[48:51], a[112:127]
	global_load_dwordx4 v[24:27], v147, s[18:19]
	s_waitcnt vmcnt(11)
	ds_write_b128 v84, v[106:109] offset:0
	s_waitcnt lgkmcnt(4)
	v_mfma_f32_32x32x16_bf16 a[16:31], v[64:67], v[44:47], a[16:31]
	ds_read_b128 v[90:93], v81 offset:0x8800
	s_waitcnt vmcnt(10)
	ds_write_b128 v84, v[110:113] offset:0x1000
	v_mfma_f32_32x32x16_bf16 a[0:15], v[64:67], v[48:51], a[0:15]
	ds_read_b128 v[94:97], v81 offset:0x9000
	s_waitcnt vmcnt(9)
	ds_write_b128 v84, v[114:117] offset:0x2000
	s_waitcnt lgkmcnt(5)
	v_mfma_f32_32x32x16_bf16 a[32:47], v[86:89], v[40:43], a[32:47]
	ds_read_b128 v[132:135], v81 offset:0x9800
	s_waitcnt vmcnt(8)
	ds_write_b128 v84, v[118:121] offset:0x3000
	v_mfma_f32_32x32x16_bf16 a[48:63], v[86:89], v[128:131], a[48:63]
	s_waitcnt vmcnt(7)
	ds_write_b128 v84, v[122:125] offset:0x4000
	s_waitcnt lgkmcnt(6)
	v_mfma_f32_32x32x16_bf16 a[64:79], v[90:93], v[40:43], a[64:79]
	s_waitcnt vmcnt(6)
	ds_write_b128 v84, v[140:143] offset:0x5000
	v_mfma_f32_32x32x16_bf16 a[80:95], v[90:93], v[128:131], a[80:95]
	s_waitcnt lgkmcnt(0)
	s_barrier
	s_mov_b32 s4, s5

.LBB0_772:
	s_abs_i32 s1, s20
	v_readlane_b32 s2, v255, 3
	s_mul_hi_u32 s2, s1, s2
	s_mul_i32 s3, s2, s5
	s_sub_i32 s1, s1, s3
	s_ashr_i32 s0, s20, 31
	s_add_i32 s3, s2, 1
	s_sub_i32 s4, s1, s5
	s_cmp_ge_u32 s1, s5
	s_cselect_b32 s2, s3, s2
	s_cselect_b32 s1, s4, s1
	s_add_i32 s3, s2, 1
	s_cmp_ge_u32 s1, s5
	s_cselect_b32 s1, s3, s2
	s_xor_b32 s1, s1, s0
	s_sub_i32 s0, s1, s0
	s_mul_hi_i32 s1, s20, 0x92492493
	s_add_i32 s1, s1, s20
	s_lshr_b32 s2, s1, 31
	s_ashr_i32 s1, s1, 2
	s_add_i32 s1, s1, s2
	s_mul_i32 s2, s1, 7
	s_mul_i32 s0, s0, 7
	s_sub_i32 s2, s20, s2
	s_add_i32 s0, s0, s2
	s_ashr_i32 s2, s1, 31
	s_abs_i32 s1, s1
	v_readlane_b32 s3, v255, 5
	s_mul_hi_u32 s3, s1, s3
	v_readlane_b32 s4, v255, 4
	s_mul_i32 s3, s3, s4
	s_sub_i32 s1, s1, s3
	s_sub_i32 s3, s1, s4
	s_cmp_ge_u32 s1, s4
	s_cselect_b32 s1, s3, s1
	s_sub_i32 s3, s1, s4
	s_cmp_ge_u32 s1, s4
	v_mov_b32_e32 v4, v208
	s_cselect_b32 s1, s3, s1
	s_lshl_b32 s0, s0, 8
	s_xor_b32 s1, s1, s2
	v_ashrrev_i32_e32 v5, 2, v4
	v_add_u32_e32 v0, s0, v5
	s_sub_i32 s1, s1, s2
	v_readlane_b32 s2, v254, 62
	v_ashrrev_i32_e32 v1, 31, v0
	s_add_i32 s1, s2, s1
	v_lshlrev_b64 v[0:1], 11, v[0:1]
	v_lshlrev_b32_e32 v6, 4, v4
	s_lshl_b32 s1, s1, 7
	v_lshl_add_u64 v[0:1], s[90:91], 0, v[0:1]
	v_and_b32_e32 v192, 48, v6
	s_waitcnt vmcnt(0)
	v_lshl_add_u64 v[64:65], v[0:1], 0, v[192:193]
	v_add_u32_e32 v0, s1, v5
	v_ashrrev_i32_e32 v1, 31, v0
	v_readlane_b32 s2, v253, 16
	v_lshlrev_b64 v[0:1], 11, v[0:1]
	v_readlane_b32 s3, v253, 17
	v_bitop3_b32 v6, v6, 48, v4 bitop3:0x48
	v_and_b32_e32 v207, 31, v4
	v_lshl_add_u64 v[0:1], s[2:3], 0, v[0:1]
	s_mov_b32 s2, 0x20000
	v_add_co_u32_e32 v8, vcc, s2, v64
	s_mov_b32 s3, 0x40000
	s_nop 0
	v_addc_co_u32_e32 v9, vcc, 0, v65, vcc
	v_add_co_u32_e32 v12, vcc, s3, v64
	v_lshrrev_b32_e32 v7, 5, v4
	s_nop 0
	v_addc_co_u32_e32 v13, vcc, 0, v65, vcc
	v_add_co_u32_e32 v16, vcc, s75, v64
	v_bfe_u32 v239, v4, 5, 1
	v_bfe_u32 v10, v4, 2, 2
	v_lshlrev_b32_e32 v11, 1, v4
	v_ashrrev_i32_e32 v4, 1, v4
	v_lshl_add_u64 v[66:67], v[0:1], 0, v[192:193]
	v_addc_co_u32_e32 v17, vcc, 0, v65, vcc
	v_and_b32_e32 v192, 0x80, v11
	v_and_b32_e32 v242, 0xffffffc0, v4
	v_add_co_u32_e32 v24, vcc, s2, v66
	v_or_b32_e32 v11, v192, v207
	v_bitop3_b32 v7, v7, v10, 1 bitop3:0x6c
	v_bitop3_b32 v10, v239, v10, 2 bitop3:0x36
	v_or_b32_e32 v4, v242, v207
	global_load_dwordx4 v[0:3], v[64:65], off
	global_load_dwordx4 v[28:31], v[8:9], off
	global_load_dwordx4 v[32:35], v[12:13], off
	global_load_dwordx4 v[36:39], v[16:17], off
	global_load_dwordx4 v[40:43], v[66:67], off
	v_addc_co_u32_e32 v25, vcc, 0, v67, vcc
	v_lshlrev_b32_e32 v11, 6, v11
	v_lshlrev_b32_e32 v7, 4, v7
	v_lshlrev_b32_e32 v10, 4, v10
	v_lshl_add_u32 v4, v4, 6, v214
	global_load_dwordx4 v[44:47], v[24:25], off
	v_or_b32_e32 v76, v11, v7
	v_or_b32_e32 v77, v11, v10
	v_or_b32_e32 v78, v4, v7
	v_or_b32_e32 v79, v4, v10
	v_lshl_or_b32 v80, v5, 6, v6
	global_load_dwordx4 v[4:7], v[64:65], off offset:64
	s_nop 0
	global_load_dwordx4 v[8:11], v[8:9], off offset:64
	s_nop 0
	global_load_dwordx4 v[12:15], v[12:13], off offset:64
	s_nop 0
	global_load_dwordx4 v[16:19], v[16:17], off offset:64
	s_nop 0
	global_load_dwordx4 v[20:23], v[66:67], off offset:64
	s_nop 0
	global_load_dwordx4 v[24:27], v[24:25], off offset:64
	v_accvgpr_mov_b32 a193, a192
	v_accvgpr_mov_b32 a194, a192
	v_accvgpr_mov_b32 a195, a192
	v_accvgpr_mov_b32 a196, a192
	v_accvgpr_mov_b32 a197, a192
	v_accvgpr_mov_b32 a198, a192
	v_accvgpr_mov_b32 a199, a192
	v_accvgpr_mov_b32 a200, a192
	v_accvgpr_mov_b32 a201, a192
	v_accvgpr_mov_b32 a202, a192
	v_accvgpr_mov_b32 a203, a192
	v_accvgpr_mov_b32 a204, a192
	v_accvgpr_mov_b32 a205, a192
	v_accvgpr_mov_b32 a206, a192
	v_accvgpr_mov_b32 a207, a192


	s_waitcnt vmcnt(11)
	ds_write_b128 v80, v[0:3] offset:0
	s_waitcnt vmcnt(10)
	ds_write_b128 v80, v[28:31] offset:0x1000
	s_waitcnt vmcnt(9)
	ds_write_b128 v80, v[32:35] offset:0x2000
	s_mov_b64 s[4:5], 0x40000
	s_mov_b64 s[6:7], 0x20000
	v_lshl_add_u64 v[70:71], v[64:65], 0, s[4:5]
	s_mov_b64 s[4:5], 0x60000
	v_mov_b32_e32 v0, 0
	s_waitcnt vmcnt(8)
	ds_write_b128 v80, v[36:39] offset:0x3000
	s_waitcnt vmcnt(7)
	ds_write_b128 v80, v[40:43] offset:0x4000
	s_waitcnt vmcnt(6)
	ds_write_b128 v80, v[44:47] offset:0x5000
	s_waitcnt lgkmcnt(0)
	v_lshl_add_u64 v[68:69], v[64:65], 0, s[6:7]
	s_mov_b32 s3, 0
	v_lshl_add_u64 v[72:73], v[64:65], 0, s[4:5]
	v_lshl_add_u64 v[74:75], v[66:67], 0, s[6:7]
	s_mov_b32 s2, -2
	v_mov_b32_e32 v1, v0
	v_mov_b32_e32 v2, v0
	v_mov_b32_e32 v3, v0
	v_mov_b32_e32 v28, v0
	v_mov_b32_e32 v29, v0
	v_mov_b32_e32 v30, v0
	v_mov_b32_e32 v31, v0
	v_mov_b32_e32 v32, v0
	v_mov_b32_e32 v33, v0
	v_mov_b32_e32 v34, v0
	v_mov_b32_e32 v35, v0
	v_mov_b32_e32 v36, v0
	v_mov_b32_e32 v37, v0
	v_mov_b32_e32 v38, v0
	v_mov_b32_e32 v39, v0
	s_barrier
.LBB0_773:
	v_readfirstlane_b32 s8, v64
	v_readfirstlane_b32 s9, v65
	v_readfirstlane_b32 s10, v68
	v_readfirstlane_b32 s11, v69
	v_readfirstlane_b32 s12, v70
	v_readfirstlane_b32 s13, v71
	v_readfirstlane_b32 s14, v72
	v_readfirstlane_b32 s15, v73
	v_readfirstlane_b32 s16, v66
	v_readfirstlane_b32 s17, v67
	v_readfirstlane_b32 s18, v74
	v_readfirstlane_b32 s19, v75
	v_subrev_u32_e32 v140, s8, v64
	v_subrev_u32_e32 v141, s16, v66
	s_nop 4
	s_add_i32 s4, s3, 64
	s_min_u32 s5, s4, 0x3e0
	s_lshl_b32 s78, s5, 1
	ds_read_b128 v[44:47], v78 offset:0
	ds_read_b128 v[40:43], v78 offset:0x800
	ds_read_b128 v[60:63], v76 offset:0
	ds_read_b128 v[56:59], v76 offset:0x800
	ds_read_b128 v[52:55], v76 offset:0x1000
	v_add_u32_e32 v142, s78, v140
	v_add_u32_e32 v143, s78, v141
	global_load_dwordx4 v[106:109], v142, s[8:9]
	ds_read_b128 v[48:51], v76 offset:0x1800
	global_load_dwordx4 v[110:113], v142, s[10:11]
	global_load_dwordx4 v[114:117], v142, s[12:13]
	s_waitcnt lgkmcnt(3)
	v_mfma_f32_32x32x16_bf16 a[112:127], v[60:63], v[44:47], 0
	ds_read_b128 v[82:85], v79 offset:0
	v_mfma_f32_32x32x16_bf16 a[96:111], v[60:63], v[40:43], 0
	global_load_dwordx4 v[118:121], v142, s[14:15]
	s_waitcnt lgkmcnt(3)
	v_mfma_f32_32x32x16_bf16 a[80:95], v[56:59], v[44:47], 0
	ds_read_b128 v[86:89], v79 offset:0x800
	v_mfma_f32_32x32x16_bf16 a[64:79], v[56:59], v[40:43], 0
	global_load_dwordx4 v[122:125], v143, s[16:17]
	s_waitcnt lgkmcnt(3)
	v_mfma_f32_32x32x16_bf16 a[48:63], v[52:55], v[44:47], 0
	ds_read_b128 v[90:93], v77 offset:0
	v_mfma_f32_32x32x16_bf16 a[16:31], v[52:55], v[40:43], 0
	global_load_dwordx4 v[126:129], v143, s[18:19]
	s_waitcnt vmcnt(11)
	ds_write_b128 v80, v[4:7] offset:0x8000
	s_waitcnt lgkmcnt(4)
	v_mfma_f32_32x32x16_bf16 a[0:15], v[48:51], v[44:47], 0
	ds_read_b128 v[94:97], v77 offset:0x800
	s_min_u32 s3, s3, 0x380
	s_lshl_b32 s78, s3, 1
	s_waitcnt vmcnt(10)
	ds_write_b128 v80, v[8:11] offset:0x9000
	v_mfma_f32_32x32x16_bf16 a[128:143], v[48:51], v[40:43], 0
	ds_read_b128 v[98:101], v77 offset:0x1000
	s_add_i32 s6, s78, 0xc0
	s_mov_b32 s7, s79
	s_waitcnt vmcnt(9)
	ds_write_b128 v80, v[12:15] offset:0xa000
	s_waitcnt lgkmcnt(5)
	v_mfma_f32_32x32x16_bf16 a[112:127], v[90:93], v[82:85], a[112:127]
	ds_read_b128 v[102:105], v77 offset:0x1800
	s_add_i32 s2, s2, 2
	s_cmp_gt_u32 s2, 29
	s_waitcnt vmcnt(8)
	ds_write_b128 v80, v[16:19] offset:0xb000
	v_mfma_f32_32x32x16_bf16 a[96:111], v[90:93], v[86:89], a[96:111]
	s_waitcnt vmcnt(7)
	ds_write_b128 v80, v[20:23] offset:0xc000
	s_waitcnt lgkmcnt(6)
	v_mfma_f32_32x32x16_bf16 a[80:95], v[94:97], v[82:85], a[80:95]
	s_waitcnt vmcnt(6)
	ds_write_b128 v80, v[24:27] offset:0xd000
	v_mfma_f32_32x32x16_bf16 a[64:79], v[94:97], v[86:89], a[64:79]
	s_waitcnt lgkmcnt(0)
	s_barrier
	ds_read_b128 v[40:43], v78 offset:0x8000
	ds_read_b128 v[44:47], v78 offset:0x8800
	ds_read_b128 v[48:51], v76 offset:0x8000
	v_mfma_f32_32x32x16_bf16 a[48:63], v[98:101], v[82:85], a[48:63]
	ds_read_b128 v[52:55], v76 offset:0x8800
	v_mfma_f32_32x32x16_bf16 a[16:31], v[98:101], v[86:89], a[16:31]
	ds_read_b128 v[56:59], v76 offset:0x9000
	v_add_u32_e32 v142, s6, v140
	v_add_u32_e32 v143, s6, v141
	global_load_dwordx4 v[4:7], v142, s[8:9]
	v_mfma_f32_32x32x16_bf16 a[0:15], v[102:105], v[82:85], a[0:15]
	ds_read_b128 v[60:63], v76 offset:0x9800
	global_load_dwordx4 v[8:11], v142, s[10:11]
	v_mfma_f32_32x32x16_bf16 a[128:143], v[102:105], v[86:89], a[128:143]
	global_load_dwordx4 v[12:15], v142, s[12:13]
	s_waitcnt lgkmcnt(3)
	v_mfma_f32_32x32x16_bf16 a[112:127], v[48:51], v[40:43], a[112:127]
	ds_read_b128 v[202:205], v79 offset:0x8000
	v_mfma_f32_32x32x16_bf16 a[96:111], v[48:51], v[44:47], a[96:111]
	global_load_dwordx4 v[16:19], v142, s[14:15]
	s_waitcnt lgkmcnt(3)
	v_mfma_f32_32x32x16_bf16 a[80:95], v[52:55], v[40:43], a[80:95]
	ds_read_b128 v[194:197], v79 offset:0x8800
	v_mfma_f32_32x32x16_bf16 a[64:79], v[52:55], v[44:47], a[64:79]
	global_load_dwordx4 v[20:23], v143, s[16:17]
	s_waitcnt lgkmcnt(3)
	v_mfma_f32_32x32x16_bf16 a[48:63], v[56:59], v[40:43], a[48:63]
	ds_read_b128 v[82:85], v77 offset:0x8000
	v_mfma_f32_32x32x16_bf16 a[16:31], v[56:59], v[44:47], a[16:31]
	global_load_dwordx4 v[24:27], v143, s[18:19]
	s_waitcnt vmcnt(11)
	ds_write_b128 v80, v[106:109] offset:0
	s_waitcnt lgkmcnt(4)
	v_mfma_f32_32x32x16_bf16 a[0:15], v[60:63], v[40:43], a[0:15]
	ds_read_b128 v[86:89], v77 offset:0x8800
	s_waitcnt vmcnt(10)
	ds_write_b128 v80, v[110:113] offset:0x1000
	v_mfma_f32_32x32x16_bf16 a[128:143], v[60:63], v[44:47], a[128:143]
	ds_read_b128 v[90:93], v77 offset:0x9000
	s_waitcnt vmcnt(9)
	ds_write_b128 v80, v[114:117] offset:0x2000
	s_waitcnt lgkmcnt(5)
	v_mfma_f32_32x32x16_bf16 a[112:127], v[82:85], v[202:205], a[112:127]
	ds_read_b128 v[198:201], v77 offset:0x9800
	s_waitcnt vmcnt(8)
	ds_write_b128 v80, v[118:121] offset:0x3000
	v_mfma_f32_32x32x16_bf16 a[96:111], v[82:85], v[194:197], a[96:111]
	s_waitcnt vmcnt(7)
	ds_write_b128 v80, v[122:125] offset:0x4000
	s_waitcnt lgkmcnt(6)
	v_mfma_f32_32x32x16_bf16 a[80:95], v[86:89], v[202:205], a[80:95]
	s_waitcnt vmcnt(6)
	ds_write_b128 v80, v[126:129] offset:0x5000
	v_mfma_f32_32x32x16_bf16 a[64:79], v[86:89], v[194:197], a[64:79]
	s_waitcnt lgkmcnt(0)
	s_barrier
	s_mov_b32 s3, s4
